# nt cache policy on once-read input streams: x rows, f32 weight tiles in the prologue, p[l] rows in the scan loop
# speedup vs baseline: 1.0028x; 1.0028x over previous
; __device__ __forceinline__ unsigned cvt_pk_bf16(float lo, float hi) { const f32x2 v = {lo, hi}; return __builtin_bit_cast(unsigned, __builtin_convertvector(v, bfx2_t)); }
; __device__ __forceinline__ float bflo(unsigned w) { return __uint_as_float(w << 16); }
; __device__ __forceinline__ float bfhi(unsigned w) { return __uint_as_float(w & 0xffff0000u); }
; __device__ __forceinline__ unsigned lo_pack4(float a, float b, float c, float d) { int p = __builtin_amdgcn_cvt_pk_fp8_f32(a * 512.0f, b * 512.0f, 0, false); return (unsigned)__builtin_amdgcn_cvt_pk_fp8_f32(c * 512.0f, d * 512.0f, p, true); }
; __device__ void prologue(const Params& P, LAS unsigned char* lds) {
;     ...
;         for (int row = blockIdx.x * 8 + wave; row < TT; row += G * 8) {
;             float ss = 0.f;
; #pragma unroll
;             for (int q = 0; q < 4; ++q) { const f32x4 v = *(const f32x4*)(x + (size_t)row * DM + q * 256 + lane * 4);
;                 ss += (v[0] * v[0] + v[1] * v[1]) + (v[2] * v[2] + v[3] * v[3]);
;                 u32x2 w; w.x = cvt_pk_bf16(v[0], v[1]); w.y = cvt_pk_bf16(v[2], v[3]); *(u32x2*)(hb + (size_t)row * DM + q * 256 + lane * 4) = w;
;                 *(unsigned*)(lo + (size_t)row * DM + q * 256 + lane * 4) = lo_pack4(v[0] - bflo(w.x), v[1] - bfhi(w.x), v[2] - bflo(w.y), v[3] - bfhi(w.y)); }
; #pragma unroll
;             for (int o = 32; o >= 1; o >>= 1) ss += __shfl_xor(ss, o);
;             if (lane < 16) ssp[(size_t)lane * TT + row] = (lane == 0) ? ss : 0.f;
;         }
.LBB0_10:
	s_waitcnt lgkmcnt(0)
	global_load_dwordx4 v[18:21], v[6:7], off offset:-3072 nt
	global_load_dwordx4 v[22:25], v[6:7], off offset:-2048 nt
	global_load_dwordx4 v[26:29], v[6:7], off offset:-1024 nt
	global_load_dwordx4 v[30:33], v[6:7], off nt
	s_load_dwordx8 s[24:31], s[0:1], 0xc0
	s_waitcnt lgkmcnt(0)
	v_lshl_add_u64 v[34:35], s[30:31], 0, v[8:9]
	s_waitcnt vmcnt(3)
	v_mul_f32_e32 v17, v19, v19
	v_mul_f32_e32 v36, v21, v21
	v_fmac_f32_e32 v17, v18, v18
	v_fmac_f32_e32 v36, v20, v20
	v_add_f32_e32 v17, v17, v36
	v_cvt_pk_bf16_f32 v18, v18, v19
	v_cvt_pk_bf16_f32 v19, v20, v21
	global_store_dwordx2 v[34:35], v[18:19], off
	s_waitcnt vmcnt(3)
	v_mul_f32_e32 v38, v23, v23
	v_mul_f32_e32 v36, v25, v25
	v_fmac_f32_e32 v38, v22, v22
	v_fmac_f32_e32 v36, v24, v24
	v_add_f32_e32 v38, v38, v36
	v_add_f32_e32 v17, v17, v38
	v_cvt_pk_bf16_f32 v22, v22, v23
	v_cvt_pk_bf16_f32 v23, v24, v25
	global_store_dwordx2 v[34:35], v[22:23], off offset:512
	s_waitcnt vmcnt(3)
	v_mul_f32_e32 v38, v27, v27
	v_mul_f32_e32 v36, v29, v29
	v_fmac_f32_e32 v38, v26, v26
	v_fmac_f32_e32 v36, v28, v28
	v_add_f32_e32 v38, v38, v36
	v_add_f32_e32 v17, v17, v38
	v_cvt_pk_bf16_f32 v26, v26, v27
	v_cvt_pk_bf16_f32 v27, v28, v29
	global_store_dwordx2 v[34:35], v[26:27], off offset:1024
	s_waitcnt vmcnt(3)
	v_mul_f32_e32 v38, v31, v31
	v_mul_f32_e32 v36, v33, v33
	v_fmac_f32_e32 v38, v30, v30
	v_fmac_f32_e32 v36, v32, v32
	v_add_f32_e32 v38, v38, v36
	v_add_f32_e32 v17, v17, v38
	v_cvt_pk_bf16_f32 v30, v30, v31
	v_cvt_pk_bf16_f32 v31, v32, v33
	global_store_dwordx2 v[34:35], v[30:31], off offset:1536
	v_mov_b32_e32 v18, v17
	s_nop 1
	v_permlane32_swap_b32_e32 v17, v18
	s_waitcnt lgkmcnt(0)
	v_add_f32_e32 v17, v17, v18
	v_mov_b32_e32 v18, v17
	s_nop 1
	v_permlane16_swap_b32_e32 v17, v18
	s_waitcnt lgkmcnt(0)
	v_add_f32_e32 v17, v17, v18
	ds_bpermute_b32 v18, v12, v17
	s_waitcnt lgkmcnt(0)
	v_add_f32_e32 v17, v17, v18
	ds_bpermute_b32 v18, v13, v17
	s_waitcnt lgkmcnt(0)
	v_add_f32_e32 v17, v17, v18
	ds_bpermute_b32 v18, v14, v17
	s_waitcnt lgkmcnt(0)
	v_add_f32_e32 v17, v17, v18
	ds_bpermute_b32 v18, v15, v17
	s_and_saveexec_b64 s[8:9], vcc
	s_cbranch_execz .LBB0_9
	s_load_dwordx8 s[24:31], s[0:1], 0xc0
	s_waitcnt lgkmcnt(0)
	v_add_f32_e32 v17, v17, v18
	v_cndmask_b32_e64 v17, 0, v17, s[6:7]
	v_lshl_add_u64 v[18:19], s[30:31], 0, v[2:3]
	global_store_dword v[18:19], v17, off
	s_branch .LBB0_9

; __device__ __forceinline__ void convT_tile(const float* src, int ldsrc, const float* sc, bf16_t* dst, int dstld, int k0, int n0, int swiglu, LAS float* t) {
;     ...
;     { const int r = tid >> 6, c4 = (tid & 63) * 4;
;       int ncol = n0 + c4; if (swiglu) { const int blk = n0 >> 8; ncol = (c4 < 128) ? (128 * blk + c4) : (FF + 128 * blk + (c4 - 128)); }
;       f32x4 v[8]; float sv[8];
; #pragma unroll
;       for (int i = 0; i < 8; ++i) { const int rr = r + 8 * i; v[i] = *(const f32x4*)(src + (size_t)(k0 + rr) * ldsrc + ncol); sv[i] = sc ? sc[k0 + rr] : 1.0f; }
.LBB0_18:
	s_ashr_i32 s0, s26, 31
	s_lshr_b32 s0, s0, 28
	s_add_i32 s0, s26, s0
	s_ashr_i32 s80, s0, 4
	s_lshl_b32 s0, s80, 7
	v_or_b32_e32 v2, s0, v45
	v_add_u32_e32 v3, s0, v47
	s_lshl_b32 s81, s80, 10
	v_cndmask_b32_e64 v2, v3, v2, s[6:7]
	s_sub_i32 s0, s39, s81
	v_ashrrev_i32_e32 v3, 31, v2
	v_add_u32_e32 v30, s0, v37
	v_lshl_add_u64 v[32:33], v[2:3], 2, s[44:45]
	v_mad_i64_i32 v[2:3], s[0:1], v30, s24, v[32:33]
	global_load_dwordx4 v[2:5], v[2:3], off nt
	v_ashrrev_i32_e32 v31, 31, v30
	v_mov_b32_e32 v42, 1.0
	v_cmp_ne_u32_e64 s[0:1], 1, v61
	s_andn2_b64 vcc, exec, s[28:29]
	v_lshl_add_u64 v[50:51], v[30:31], 2, s[64:65]
	v_mov_b32_e32 v46, 1.0
	s_cbranch_vccnz .LBB0_20
	global_load_dword v46, v[50:51], off
.LBB0_20:
	v_add_u32_e32 v6, 8, v30
	v_mad_i64_i32 v[6:7], s[82:83], v6, s24, v[32:33]
	global_load_dwordx4 v[6:9], v[6:7], off nt
	s_and_b64 vcc, exec, s[0:1]
	s_cbranch_vccnz .LBB0_22
	global_load_dword v42, v[50:51], off offset:32
.LBB0_22:
	v_add_u32_e32 v10, 16, v30
	v_mad_i64_i32 v[10:11], s[82:83], v10, s24, v[32:33]
	global_load_dwordx4 v[10:13], v[10:11], off nt
	v_mov_b32_e32 v44, 1.0
	s_and_b64 vcc, exec, s[0:1]
	v_mov_b32_e32 v52, 1.0
	s_cbranch_vccnz .LBB0_24
	global_load_dword v52, v[50:51], off offset:64
.LBB0_24:
	v_add_u32_e32 v14, 24, v30
	v_mad_i64_i32 v[14:15], s[82:83], v14, s24, v[32:33]
	global_load_dwordx4 v[14:17], v[14:15], off nt
	s_and_b64 vcc, exec, s[0:1]
	s_cbranch_vccnz .LBB0_26
	global_load_dword v44, v[50:51], off offset:96
.LBB0_26:
	v_add_u32_e32 v18, 32, v30
	v_mad_i64_i32 v[18:19], s[82:83], v18, s24, v[32:33]
	global_load_dwordx4 v[18:21], v[18:19], off nt
	v_mov_b32_e32 v48, 1.0
	s_and_b64 vcc, exec, s[0:1]
	v_mov_b32_e32 v56, 1.0
	s_cbranch_vccnz .LBB0_28
	global_load_dword v56, v[50:51], off offset:128
.LBB0_28:
	v_add_u32_e32 v22, 40, v30
	v_mad_i64_i32 v[22:23], s[82:83], v22, s24, v[32:33]
	global_load_dwordx4 v[22:25], v[22:23], off nt
	s_and_b64 vcc, exec, s[0:1]
	s_cbranch_vccnz .LBB0_30
	global_load_dword v48, v[50:51], off offset:160
.LBB0_30:
	v_add_u32_e32 v26, 48, v30
	v_mad_i64_i32 v[26:27], s[82:83], v26, s24, v[32:33]
	global_load_dwordx4 v[26:29], v[26:27], off nt
	v_mov_b32_e32 v54, 1.0
	s_and_b64 vcc, exec, s[0:1]
	v_mov_b32_e32 v58, 1.0
	s_cbranch_vccnz .LBB0_32
	global_load_dword v58, v[50:51], off offset:192
.LBB0_32:
	v_add_u32_e32 v30, 56, v30
	v_mad_i64_i32 v[30:31], s[82:83], v30, s24, v[32:33]
	global_load_dwordx4 v[30:33], v[30:31], off nt
	s_and_b64 vcc, exec, s[0:1]
	s_sub_i32 s0, 0, s81
	s_cbranch_vccnz .LBB0_17
	global_load_dword v54, v[50:51], off offset:224
	s_branch .LBB0_17

; #define LAS __attribute__((address_space(3)))
; __device__ __forceinline__ unsigned cvt_pk_bf16(float lo, float hi) { const f32x2 v = {lo, hi}; return __builtin_bit_cast(unsigned, __builtin_convertvector(v, bfx2_t)); }
; __device__ __forceinline__ void convT_tile(const float* src, int ldsrc, const float* sc, bf16_t* dst, int dstld, int k0, int n0, int swiglu, LAS float* t) {
;     const int tid = threadIdx.x;
;     { const int r = tid >> 6, c4 = (tid & 63) * 4;
;       int ncol = n0 + c4; if (swiglu) { const int blk = n0 >> 8; ncol = (c4 < 128) ? (128 * blk + c4) : (FF + 128 * blk + (c4 - 128)); }
;       f32x4 v[8]; float sv[8];
; #pragma unroll
;       for (int i = 0; i < 8; ++i) { const int rr = r + 8 * i; v[i] = *(const f32x4*)(src + (size_t)(k0 + rr) * ldsrc + ncol); sv[i] = sc ? sc[k0 + rr] : 1.0f; }
; #pragma unroll
;       for (int i = 0; i < 8; ++i) { const int rr = r + 8 * i; t[rr * 257 + c4 + 0] = v[i][0] * sv[i]; t[rr * 257 + c4 + 1] = v[i][1] * sv[i]; t[rr * 257 + c4 + 2] = v[i][2] * sv[i]; t[rr * 257 + c4 + 3] = v[i][3] * sv[i]; } }
;     __syncthreads();
;     { const int nn = tid >> 1, kh = (tid & 1) * 32;
; #pragma unroll
;       for (int q = 0; q < 4; ++q) { float v[8];
; #pragma unroll
;           for (int j = 0; j < 8; ++j) v[j] = t[(kh + q * 8 + j) * 257 + nn];
;           u32x4 w; w.x = cvt_pk_bf16(v[0], v[1]); w.y = cvt_pk_bf16(v[2], v[3]); w.z = cvt_pk_bf16(v[4], v[5]); w.w = cvt_pk_bf16(v[6], v[7]);
;           *(u32x4*)(dst + (size_t)(n0 + nn) * dstld + k0 + kh + q * 8) = w; } }
;     __syncthreads();
; }
.LBB0_36:
	s_mul_hi_i32 s80, s26, 0x2e8ba2e9
	s_lshr_b32 s81, s80, 31
	s_ashr_i32 s80, s80, 3
	s_add_i32 s80, s80, s81
	s_mul_i32 s81, s80, 0xfffff500
	s_lshl_b32 s80, s80, 8
	s_add_i32 s90, s92, s81
	v_or_b32_e32 v2, s80, v45
	v_add_u32_e32 v4, s90, v37
	v_ashrrev_i32_e32 v3, 31, v2
	v_lshl_add_u64 v[6:7], v[2:3], 2, s[0:1]
	v_add_u32_e32 v2, 8, v4
	v_add_u32_e32 v8, 16, v4
	v_add_u32_e32 v10, 24, v4
	v_add_u32_e32 v12, 32, v4
	v_add_u32_e32 v14, 40, v4
	v_add_u32_e32 v16, 48, v4
	v_add_u32_e32 v18, 56, v4
	v_ashrrev_i32_e32 v5, 31, v4
	v_ashrrev_i32_e32 v3, 31, v2
	v_ashrrev_i32_e32 v9, 31, v8
	v_ashrrev_i32_e32 v11, 31, v10
	v_ashrrev_i32_e32 v13, 31, v12
	v_ashrrev_i32_e32 v15, 31, v14
	v_ashrrev_i32_e32 v17, 31, v16
	v_ashrrev_i32_e32 v19, 31, v18
	v_lshlrev_b64 v[4:5], 12, v[4:5]
	v_lshlrev_b64 v[20:21], 12, v[2:3]
	v_lshlrev_b64 v[8:9], 12, v[8:9]
	v_lshlrev_b64 v[10:11], 12, v[10:11]
	v_lshlrev_b64 v[12:13], 12, v[12:13]
	v_lshlrev_b64 v[14:15], 12, v[14:15]
	v_lshlrev_b64 v[16:17], 12, v[16:17]
	v_lshlrev_b64 v[18:19], 12, v[18:19]
	v_lshl_add_u64 v[4:5], v[6:7], 0, v[4:5]
	v_lshl_add_u64 v[20:21], v[6:7], 0, v[20:21]
	v_lshl_add_u64 v[22:23], v[6:7], 0, v[8:9]
	v_lshl_add_u64 v[24:25], v[6:7], 0, v[10:11]
	v_lshl_add_u64 v[26:27], v[6:7], 0, v[12:13]
	v_lshl_add_u64 v[28:29], v[6:7], 0, v[14:15]
	v_lshl_add_u64 v[30:31], v[6:7], 0, v[16:17]
	v_lshl_add_u64 v[32:33], v[6:7], 0, v[18:19]
	global_load_dwordx4 v[2:5], v[4:5], off nt
	s_nop 0
	global_load_dwordx4 v[6:9], v[20:21], off nt
	global_load_dwordx4 v[10:13], v[22:23], off nt
	global_load_dwordx4 v[14:17], v[24:25], off nt
	s_nop 0
	global_load_dwordx4 v[18:21], v[26:27], off nt
	global_load_dwordx4 v[22:25], v[28:29], off nt
	s_nop 0
	global_load_dwordx4 v[26:29], v[30:31], off nt
	s_nop 0
	global_load_dwordx4 v[30:33], v[32:33], off nt
	v_add_u32_e32 v41, 0x2020, v53
	v_add_u32_e32 v42, 0x2028, v53
	v_add_u32_e32 v44, 0x4040, v53
	v_add_u32_e32 v46, 0x4048, v53
	v_add_u32_e32 v50, 0x6060, v53
	v_add_u32_e32 v51, 0x6068, v53
	v_add_u32_e32 v52, 0x8080, v53
	v_add_u32_e32 v54, 0x8088, v53
	v_add_u32_e32 v56, 0xa0a0, v53
	v_add_u32_e32 v58, 0xa0a8, v53
	v_add_u32_e32 v65, 0xc0c0, v53
	v_add_u32_e32 v66, 0xc0c8, v53
	v_add_u32_e32 v67, 0xe0e0, v53
	v_add_u32_e32 v68, 0xe0e8, v53
	v_mov_b64_e32 v[48:49], s[44:45]
	v_add_u32_e32 v69, s80, v55
	v_mad_i64_i32 v[48:49], s[80:81], v69, s25, v[48:49]
	s_ashr_i32 s91, s90, 31
	s_add_i32 s26, s26, s88
	s_add_i32 s92, s92, s5
	v_lshl_add_u64 v[48:49], s[90:91], 1, v[48:49]
	s_cmpk_lt_i32 s26, 0xb0
	v_lshl_add_u64 v[48:49], v[48:49], 0, v[34:35]
	s_waitcnt vmcnt(7)
	ds_write2_b32 v53, v2, v3 offset1:1
	ds_write2_b32 v53, v4, v5 offset0:2 offset1:3
	s_waitcnt vmcnt(6)
	ds_write2_b32 v41, v6, v7 offset1:1
	ds_write2_b32 v42, v8, v9 offset1:1
	s_waitcnt vmcnt(5)
	ds_write2_b32 v44, v10, v11 offset1:1
	ds_write2_b32 v46, v12, v13 offset1:1
	s_waitcnt vmcnt(4)
	ds_write2_b32 v50, v14, v15 offset1:1
	ds_write2_b32 v51, v16, v17 offset1:1
	s_waitcnt vmcnt(3)
	ds_write2_b32 v52, v18, v19 offset1:1
	ds_write2_b32 v54, v20, v21 offset1:1
	s_waitcnt vmcnt(2)
	ds_write2_b32 v56, v22, v23 offset1:1
	ds_write2_b32 v58, v24, v25 offset1:1
	s_waitcnt vmcnt(1)
	ds_write2_b32 v65, v26, v27 offset1:1
	ds_write2_b32 v66, v28, v29 offset1:1
	s_waitcnt vmcnt(0)
	ds_write2_b32 v67, v30, v31 offset1:1
	ds_write2_b32 v68, v32, v33 offset1:1
	s_waitcnt lgkmcnt(0)
	s_barrier
	ds_read_b32 v2, v57
	ds_read_b32 v3, v57 offset:1028
	ds_read_b32 v4, v57 offset:2056
	ds_read_b32 v5, v57 offset:3084
	ds_read_b32 v6, v57 offset:4112
	ds_read_b32 v7, v57 offset:5140
	ds_read_b32 v8, v57 offset:6168
	ds_read_b32 v9, v57 offset:7196
	ds_read_b32 v10, v57 offset:8224
	ds_read_b32 v11, v57 offset:9252
	ds_read_b32 v12, v57 offset:10280
	ds_read_b32 v13, v57 offset:11308
	ds_read_b32 v14, v57 offset:12336
	ds_read_b32 v15, v57 offset:13364
	ds_read_b32 v16, v57 offset:14392
	ds_read_b32 v17, v57 offset:15420
	ds_read_b32 v18, v57 offset:16448
	ds_read_b32 v19, v57 offset:17476
	ds_read_b32 v20, v57 offset:18504
	ds_read_b32 v21, v57 offset:19532
	ds_read_b32 v22, v57 offset:20560
	ds_read_b32 v23, v57 offset:21588
	ds_read_b32 v24, v57 offset:22616
	ds_read_b32 v25, v57 offset:23644
	ds_read_b32 v26, v57 offset:24672
	ds_read_b32 v27, v57 offset:25700
	ds_read_b32 v28, v57 offset:26728
	ds_read_b32 v29, v57 offset:27756
	ds_read_b32 v30, v57 offset:28784
	ds_read_b32 v31, v57 offset:29812
	ds_read_b32 v32, v57 offset:30840
	ds_read_b32 v33, v57 offset:31868
	s_waitcnt lgkmcnt(14)
	v_cvt_pk_bf16_f32 v2, v2, v3
	v_cvt_pk_bf16_f32 v3, v4, v5
	v_cvt_pk_bf16_f32 v4, v6, v7
	v_cvt_pk_bf16_f32 v5, v8, v9
	v_cvt_pk_bf16_f32 v6, v10, v11
	v_cvt_pk_bf16_f32 v7, v12, v13
	v_cvt_pk_bf16_f32 v8, v14, v15
	v_cvt_pk_bf16_f32 v9, v16, v17
	v_cvt_pk_bf16_f32 v10, v18, v19
	s_waitcnt lgkmcnt(12)
	v_cvt_pk_bf16_f32 v11, v20, v21
	s_waitcnt lgkmcnt(10)
	v_cvt_pk_bf16_f32 v12, v22, v23
	s_waitcnt lgkmcnt(8)
	v_cvt_pk_bf16_f32 v13, v24, v25
	s_waitcnt lgkmcnt(6)
	v_cvt_pk_bf16_f32 v14, v26, v27
	s_waitcnt lgkmcnt(4)
	v_cvt_pk_bf16_f32 v15, v28, v29
	s_waitcnt lgkmcnt(2)
	v_cvt_pk_bf16_f32 v16, v30, v31
	s_waitcnt lgkmcnt(0)
	v_cvt_pk_bf16_f32 v17, v32, v33
	global_store_dwordx4 v[48:49], v[2:5], off
	global_store_dwordx4 v[48:49], v[6:9], off offset:16
	global_store_dwordx4 v[48:49], v[10:13], off offset:32
	global_store_dwordx4 v[48:49], v[14:17], off offset:48
	s_barrier
	s_cbranch_scc1 .LBB0_36

; __device__ __forceinline__ void convT_tile(const float* src, int ldsrc, const float* sc, bf16_t* dst, int dstld, int k0, int n0, int swiglu, LAS float* t) {
;     ...
;     { const int r = tid >> 6, c4 = (tid & 63) * 4;
;       int ncol = n0 + c4; if (swiglu) { const int blk = n0 >> 8; ncol = (c4 < 128) ? (128 * blk + c4) : (FF + 128 * blk + (c4 - 128)); }
;       f32x4 v[8]; float sv[8];
; #pragma unroll
;       for (int i = 0; i < 8; ++i) { const int rr = r + 8 * i; v[i] = *(const f32x4*)(src + (size_t)(k0 + rr) * ldsrc + ncol); sv[i] = sc ? sc[k0 + rr] : 1.0f; }
.LBB0_40:
	s_ashr_i32 s0, s26, 31
	s_lshr_b32 s0, s0, 28
	s_add_i32 s0, s26, s0
	s_ashr_i32 s0, s0, 4
	s_lshl_b32 s81, s0, 10
	s_lshl_b32 s80, s0, 8
	s_sub_i32 s0, s39, s81
	v_or_b32_e32 v2, s80, v45
	v_add_u32_e32 v32, s0, v37
	v_ashrrev_i32_e32 v3, 31, v2
	v_ashrrev_i32_e32 v33, 31, v32
	v_lshl_add_u64 v[30:31], v[2:3], 2, s[90:91]
	v_lshlrev_b64 v[2:3], 12, v[32:33]
	v_lshl_add_u64 v[2:3], v[30:31], 0, v[2:3]
	global_load_dwordx4 v[2:5], v[2:3], off nt
	v_cndmask_b32_e64 v6, 0, 1, s[30:31]
	v_mov_b32_e32 v42, 1.0
	v_cmp_ne_u32_e64 s[0:1], 1, v6
	s_andn2_b64 vcc, exec, s[30:31]
	v_lshl_add_u64 v[48:49], v[32:33], 2, s[92:93]
	v_mov_b32_e32 v44, 1.0
	s_cbranch_vccnz .LBB0_42
	global_load_dword v44, v[48:49], off
.LBB0_42:
	v_add_u32_e32 v6, 8, v32
	v_ashrrev_i32_e32 v7, 31, v6
	v_lshlrev_b64 v[6:7], 12, v[6:7]
	v_lshl_add_u64 v[6:7], v[30:31], 0, v[6:7]
	global_load_dwordx4 v[6:9], v[6:7], off nt
	s_and_b64 vcc, exec, s[0:1]
	s_cbranch_vccnz .LBB0_44
	global_load_dword v42, v[48:49], off offset:32
.LBB0_44:
	v_add_u32_e32 v10, 16, v32
	v_ashrrev_i32_e32 v11, 31, v10
	v_lshlrev_b64 v[10:11], 12, v[10:11]
	v_lshl_add_u64 v[10:11], v[30:31], 0, v[10:11]
	global_load_dwordx4 v[10:13], v[10:11], off nt
	v_mov_b32_e32 v46, 1.0
	s_and_b64 vcc, exec, s[0:1]
	v_mov_b32_e32 v50, 1.0
	s_cbranch_vccnz .LBB0_46
	global_load_dword v50, v[48:49], off offset:64
.LBB0_46:
	v_add_u32_e32 v14, 24, v32
	v_ashrrev_i32_e32 v15, 31, v14
	v_lshlrev_b64 v[14:15], 12, v[14:15]
	v_lshl_add_u64 v[14:15], v[30:31], 0, v[14:15]
	global_load_dwordx4 v[14:17], v[14:15], off nt
	s_and_b64 vcc, exec, s[0:1]
	s_cbranch_vccnz .LBB0_48
	global_load_dword v46, v[48:49], off offset:96
.LBB0_48:
	v_add_u32_e32 v18, 32, v32
	v_ashrrev_i32_e32 v19, 31, v18
	v_lshlrev_b64 v[18:19], 12, v[18:19]
	v_lshl_add_u64 v[18:19], v[30:31], 0, v[18:19]
	global_load_dwordx4 v[18:21], v[18:19], off nt
	v_mov_b32_e32 v52, 1.0
	s_and_b64 vcc, exec, s[0:1]
	v_mov_b32_e32 v54, 1.0
	s_cbranch_vccnz .LBB0_50
	global_load_dword v54, v[48:49], off offset:128
.LBB0_50:
	v_add_u32_e32 v22, 40, v32
	v_ashrrev_i32_e32 v23, 31, v22
	v_lshlrev_b64 v[22:23], 12, v[22:23]
	v_lshl_add_u64 v[22:23], v[30:31], 0, v[22:23]
	global_load_dwordx4 v[22:25], v[22:23], off nt
	s_and_b64 vcc, exec, s[0:1]
	s_cbranch_vccnz .LBB0_52
	global_load_dword v52, v[48:49], off offset:160
.LBB0_52:
	v_add_u32_e32 v26, 48, v32
	v_ashrrev_i32_e32 v27, 31, v26
	v_lshlrev_b64 v[26:27], 12, v[26:27]
	v_lshl_add_u64 v[26:27], v[30:31], 0, v[26:27]
	global_load_dwordx4 v[26:29], v[26:27], off nt
	v_mov_b32_e32 v56, 1.0
	s_and_b64 vcc, exec, s[0:1]
	v_mov_b32_e32 v58, 1.0
	s_cbranch_vccnz .LBB0_54
	global_load_dword v58, v[48:49], off offset:192
.LBB0_54:
	v_add_u32_e32 v32, 56, v32
	v_ashrrev_i32_e32 v33, 31, v32
	v_lshlrev_b64 v[32:33], 12, v[32:33]
	v_lshl_add_u64 v[30:31], v[30:31], 0, v[32:33]
	global_load_dwordx4 v[30:33], v[30:31], off nt
	s_and_b64 vcc, exec, s[0:1]
	s_sub_i32 s0, 0, s81
	s_cbranch_vccnz .LBB0_39
	global_load_dword v56, v[48:49], off offset:224
	s_branch .LBB0_39

; #define LAS __attribute__((address_space(3)))
; __device__ __forceinline__ unsigned cvt_pk_bf16(float lo, float hi) { const f32x2 v = {lo, hi}; return __builtin_bit_cast(unsigned, __builtin_convertvector(v, bfx2_t)); }
; __device__ __forceinline__ void convT_tile(const float* src, int ldsrc, const float* sc, bf16_t* dst, int dstld, int k0, int n0, int swiglu, LAS float* t) {
;     const int tid = threadIdx.x;
;     { const int r = tid >> 6, c4 = (tid & 63) * 4;
;       int ncol = n0 + c4; if (swiglu) { const int blk = n0 >> 8; ncol = (c4 < 128) ? (128 * blk + c4) : (FF + 128 * blk + (c4 - 128)); }
;       f32x4 v[8]; float sv[8];
; #pragma unroll
;       for (int i = 0; i < 8; ++i) { const int rr = r + 8 * i; v[i] = *(const f32x4*)(src + (size_t)(k0 + rr) * ldsrc + ncol); sv[i] = sc ? sc[k0 + rr] : 1.0f; }
; #pragma unroll
;       for (int i = 0; i < 8; ++i) { const int rr = r + 8 * i; t[rr * 257 + c4 + 0] = v[i][0] * sv[i]; t[rr * 257 + c4 + 1] = v[i][1] * sv[i]; t[rr * 257 + c4 + 2] = v[i][2] * sv[i]; t[rr * 257 + c4 + 3] = v[i][3] * sv[i]; } }
;     __syncthreads();
;     { const int nn = tid >> 1, kh = (tid & 1) * 32;
; #pragma unroll
;       for (int q = 0; q < 4; ++q) { float v[8];
; #pragma unroll
;           for (int j = 0; j < 8; ++j) v[j] = t[(kh + q * 8 + j) * 257 + nn];
;           u32x4 w; w.x = cvt_pk_bf16(v[0], v[1]); w.y = cvt_pk_bf16(v[2], v[3]); w.z = cvt_pk_bf16(v[4], v[5]); w.w = cvt_pk_bf16(v[6], v[7]);
;           *(u32x4*)(dst + (size_t)(n0 + nn) * dstld + k0 + kh + q * 8) = w; } }
;     __syncthreads();
; }
.LBB0_58:
	s_ashr_i32 s80, s26, 31
	s_lshr_b32 s80, s80, 29
	s_add_i32 s80, s26, s80
	s_ashr_i32 s80, s80, 3
	s_lshl_b32 s81, s80, 9
	s_lshl_b32 s80, s80, 8
	s_sub_i32 s92, s39, s81
	v_or_b32_e32 v2, s80, v45
	v_add_u32_e32 v4, s92, v37
	v_ashrrev_i32_e32 v3, 31, v2
	v_lshl_add_u64 v[6:7], v[2:3], 2, s[0:1]
	v_add_u32_e32 v2, 8, v4
	v_add_u32_e32 v8, 16, v4
	v_add_u32_e32 v10, 24, v4
	v_add_u32_e32 v12, 32, v4
	v_add_u32_e32 v14, 40, v4
	v_add_u32_e32 v16, 48, v4
	v_add_u32_e32 v18, 56, v4
	v_ashrrev_i32_e32 v5, 31, v4
	v_ashrrev_i32_e32 v3, 31, v2
	v_ashrrev_i32_e32 v9, 31, v8
	v_ashrrev_i32_e32 v11, 31, v10
	v_ashrrev_i32_e32 v13, 31, v12
	v_ashrrev_i32_e32 v15, 31, v14
	v_ashrrev_i32_e32 v17, 31, v16
	v_ashrrev_i32_e32 v19, 31, v18
	v_lshlrev_b64 v[4:5], 11, v[4:5]
	v_lshlrev_b64 v[20:21], 11, v[2:3]
	v_lshlrev_b64 v[8:9], 11, v[8:9]
	v_lshlrev_b64 v[10:11], 11, v[10:11]
	v_lshlrev_b64 v[12:13], 11, v[12:13]
	v_lshlrev_b64 v[14:15], 11, v[14:15]
	v_lshlrev_b64 v[16:17], 11, v[16:17]
	v_lshlrev_b64 v[18:19], 11, v[18:19]
	v_lshl_add_u64 v[4:5], v[6:7], 0, v[4:5]
	v_lshl_add_u64 v[20:21], v[6:7], 0, v[20:21]
	v_lshl_add_u64 v[22:23], v[6:7], 0, v[8:9]
	v_lshl_add_u64 v[24:25], v[6:7], 0, v[10:11]
	v_lshl_add_u64 v[26:27], v[6:7], 0, v[12:13]
	v_lshl_add_u64 v[28:29], v[6:7], 0, v[14:15]
	v_lshl_add_u64 v[30:31], v[6:7], 0, v[16:17]
	v_lshl_add_u64 v[32:33], v[6:7], 0, v[18:19]
	global_load_dwordx4 v[2:5], v[4:5], off nt
	s_nop 0
	global_load_dwordx4 v[6:9], v[20:21], off nt
	global_load_dwordx4 v[10:13], v[22:23], off nt
	global_load_dwordx4 v[14:17], v[24:25], off nt
	s_nop 0
	global_load_dwordx4 v[18:21], v[26:27], off nt
	global_load_dwordx4 v[22:25], v[28:29], off nt
	s_nop 0
	global_load_dwordx4 v[26:29], v[30:31], off nt
	s_nop 0
	global_load_dwordx4 v[30:33], v[32:33], off nt
	v_add_u32_e32 v48, s80, v55
	v_add_u32_e32 v41, 0x2020, v53
	v_add_u32_e32 v42, 0x2028, v53
	v_add_u32_e32 v44, 0x4040, v53
	v_add_u32_e32 v46, 0x4048, v53
	v_add_u32_e32 v50, 0x6060, v53
	v_add_u32_e32 v51, 0x6068, v53
	v_add_u32_e32 v52, 0x8080, v53
	v_add_u32_e32 v54, 0x8088, v53
	v_add_u32_e32 v56, 0xa0a0, v53
	v_add_u32_e32 v58, 0xa0a8, v53
	v_add_u32_e32 v65, 0xc0c0, v53
	v_add_u32_e32 v66, 0xc0c8, v53
	v_add_u32_e32 v67, 0xe0e0, v53
	v_add_u32_e32 v68, 0xe0e8, v53
	v_ashrrev_i32_e32 v49, 31, v48
	v_lshlrev_b64 v[48:49], 10, v[48:49]
	s_ashr_i32 s93, s92, 31
	v_lshl_add_u64 v[48:49], s[90:91], 0, v[48:49]
	s_add_i32 s26, s26, s88
	s_add_i32 s39, s39, s5
	v_lshl_add_u64 v[48:49], s[92:93], 1, v[48:49]
	s_cmp_lt_i32 s26, 16
	v_lshl_add_u64 v[48:49], v[48:49], 0, v[34:35]
	s_waitcnt vmcnt(7)
	ds_write2_b32 v53, v2, v3 offset1:1
	ds_write2_b32 v53, v4, v5 offset0:2 offset1:3
	s_waitcnt vmcnt(6)
	ds_write2_b32 v41, v6, v7 offset1:1
	ds_write2_b32 v42, v8, v9 offset1:1
	s_waitcnt vmcnt(5)
	ds_write2_b32 v44, v10, v11 offset1:1
	ds_write2_b32 v46, v12, v13 offset1:1
	s_waitcnt vmcnt(4)
	ds_write2_b32 v50, v14, v15 offset1:1
	ds_write2_b32 v51, v16, v17 offset1:1
	s_waitcnt vmcnt(3)
	ds_write2_b32 v52, v18, v19 offset1:1
	ds_write2_b32 v54, v20, v21 offset1:1
	s_waitcnt vmcnt(2)
	ds_write2_b32 v56, v22, v23 offset1:1
	ds_write2_b32 v58, v24, v25 offset1:1
	s_waitcnt vmcnt(1)
	ds_write2_b32 v65, v26, v27 offset1:1
	ds_write2_b32 v66, v28, v29 offset1:1
	s_waitcnt vmcnt(0)
	ds_write2_b32 v67, v30, v31 offset1:1
	ds_write2_b32 v68, v32, v33 offset1:1
	s_waitcnt lgkmcnt(0)
	s_barrier
	ds_read_b32 v2, v57
	ds_read_b32 v3, v57 offset:1028
	ds_read_b32 v4, v57 offset:2056
	ds_read_b32 v5, v57 offset:3084
	ds_read_b32 v6, v57 offset:4112
	ds_read_b32 v7, v57 offset:5140
	ds_read_b32 v8, v57 offset:6168
	ds_read_b32 v9, v57 offset:7196
	ds_read_b32 v10, v57 offset:8224
	ds_read_b32 v11, v57 offset:9252
	ds_read_b32 v12, v57 offset:10280
	ds_read_b32 v13, v57 offset:11308
	ds_read_b32 v14, v57 offset:12336
	ds_read_b32 v15, v57 offset:13364
	ds_read_b32 v16, v57 offset:14392
	ds_read_b32 v17, v57 offset:15420
	ds_read_b32 v18, v57 offset:16448
	ds_read_b32 v19, v57 offset:17476
	ds_read_b32 v20, v57 offset:18504
	ds_read_b32 v21, v57 offset:19532
	ds_read_b32 v22, v57 offset:20560
	ds_read_b32 v23, v57 offset:21588
	ds_read_b32 v24, v57 offset:22616
	ds_read_b32 v25, v57 offset:23644
	ds_read_b32 v26, v57 offset:24672
	ds_read_b32 v27, v57 offset:25700
	ds_read_b32 v28, v57 offset:26728
	ds_read_b32 v29, v57 offset:27756
	ds_read_b32 v30, v57 offset:28784
	ds_read_b32 v31, v57 offset:29812
	ds_read_b32 v32, v57 offset:30840
	ds_read_b32 v33, v57 offset:31868
	s_waitcnt lgkmcnt(14)
	v_cvt_pk_bf16_f32 v2, v2, v3
	v_cvt_pk_bf16_f32 v3, v4, v5
	v_cvt_pk_bf16_f32 v4, v6, v7
	v_cvt_pk_bf16_f32 v5, v8, v9
	v_cvt_pk_bf16_f32 v6, v10, v11
	v_cvt_pk_bf16_f32 v7, v12, v13
	v_cvt_pk_bf16_f32 v8, v14, v15
	v_cvt_pk_bf16_f32 v9, v16, v17
	v_cvt_pk_bf16_f32 v10, v18, v19
	s_waitcnt lgkmcnt(12)
	v_cvt_pk_bf16_f32 v11, v20, v21
	s_waitcnt lgkmcnt(10)
	v_cvt_pk_bf16_f32 v12, v22, v23
	s_waitcnt lgkmcnt(8)
	v_cvt_pk_bf16_f32 v13, v24, v25
	s_waitcnt lgkmcnt(6)
	v_cvt_pk_bf16_f32 v14, v26, v27
	s_waitcnt lgkmcnt(4)
	v_cvt_pk_bf16_f32 v15, v28, v29
	s_waitcnt lgkmcnt(2)
	v_cvt_pk_bf16_f32 v16, v30, v31
	s_waitcnt lgkmcnt(0)
	v_cvt_pk_bf16_f32 v17, v32, v33
	global_store_dwordx4 v[48:49], v[2:5], off
	global_store_dwordx4 v[48:49], v[6:9], off offset:16
	global_store_dwordx4 v[48:49], v[10:13], off offset:32
	global_store_dwordx4 v[48:49], v[14:17], off offset:48
	s_barrier
	s_cbranch_scc1 .LBB0_58

; #define LAS __attribute__((address_space(3)))
; __device__ __forceinline__ unsigned cvt_pk_bf16(float lo, float hi) { const f32x2 v = {lo, hi}; return __builtin_bit_cast(unsigned, __builtin_convertvector(v, bfx2_t)); }
; __device__ __forceinline__ void convT_tile(const float* src, int ldsrc, const float* sc, bf16_t* dst, int dstld, int k0, int n0, int swiglu, LAS float* t) {
;     const int tid = threadIdx.x;
;     { const int r = tid >> 6, c4 = (tid & 63) * 4;
;       int ncol = n0 + c4; if (swiglu) { const int blk = n0 >> 8; ncol = (c4 < 128) ? (128 * blk + c4) : (FF + 128 * blk + (c4 - 128)); }
;       f32x4 v[8]; float sv[8];
; #pragma unroll
;       for (int i = 0; i < 8; ++i) { const int rr = r + 8 * i; v[i] = *(const f32x4*)(src + (size_t)(k0 + rr) * ldsrc + ncol); sv[i] = sc ? sc[k0 + rr] : 1.0f; }
; #pragma unroll
;       for (int i = 0; i < 8; ++i) { const int rr = r + 8 * i; t[rr * 257 + c4 + 0] = v[i][0] * sv[i]; t[rr * 257 + c4 + 1] = v[i][1] * sv[i]; t[rr * 257 + c4 + 2] = v[i][2] * sv[i]; t[rr * 257 + c4 + 3] = v[i][3] * sv[i]; } }
;     __syncthreads();
;     { const int nn = tid >> 1, kh = (tid & 1) * 32;
; #pragma unroll
;       for (int q = 0; q < 4; ++q) { float v[8];
; #pragma unroll
;           for (int j = 0; j < 8; ++j) v[j] = t[(kh + q * 8 + j) * 257 + nn];
;           u32x4 w; w.x = cvt_pk_bf16(v[0], v[1]); w.y = cvt_pk_bf16(v[2], v[3]); w.z = cvt_pk_bf16(v[4], v[5]); w.w = cvt_pk_bf16(v[6], v[7]);
;           *(u32x4*)(dst + (size_t)(n0 + nn) * dstld + k0 + kh + q * 8) = w; } }
;     __syncthreads();
; }
.LBB0_61:
	s_ashr_i32 s80, s26, 31
	s_lshr_b32 s80, s80, 29
	s_add_i32 s80, s26, s80
	s_ashr_i32 s80, s80, 3
	s_lshl_b32 s81, s80, 9
	s_lshl_b32 s80, s80, 8
	s_sub_i32 s92, s39, s81
	v_or_b32_e32 v2, s80, v45
	v_add_u32_e32 v4, s92, v37
	v_ashrrev_i32_e32 v3, 31, v2
	v_lshl_add_u64 v[6:7], v[2:3], 2, s[0:1]
	v_add_u32_e32 v2, 8, v4
	v_add_u32_e32 v8, 16, v4
	v_add_u32_e32 v10, 24, v4
	v_add_u32_e32 v12, 32, v4
	v_add_u32_e32 v14, 40, v4
	v_add_u32_e32 v16, 48, v4
	v_add_u32_e32 v18, 56, v4
	v_ashrrev_i32_e32 v5, 31, v4
	v_ashrrev_i32_e32 v3, 31, v2
	v_ashrrev_i32_e32 v9, 31, v8
	v_ashrrev_i32_e32 v11, 31, v10
	v_ashrrev_i32_e32 v13, 31, v12
	v_ashrrev_i32_e32 v15, 31, v14
	v_ashrrev_i32_e32 v17, 31, v16
	v_ashrrev_i32_e32 v19, 31, v18
	v_lshlrev_b64 v[4:5], 12, v[4:5]
	v_lshlrev_b64 v[20:21], 12, v[2:3]
	v_lshlrev_b64 v[8:9], 12, v[8:9]
	v_lshlrev_b64 v[10:11], 12, v[10:11]
	v_lshlrev_b64 v[12:13], 12, v[12:13]
	v_lshlrev_b64 v[14:15], 12, v[14:15]
	v_lshlrev_b64 v[16:17], 12, v[16:17]
	v_lshlrev_b64 v[18:19], 12, v[18:19]
	v_lshl_add_u64 v[4:5], v[6:7], 0, v[4:5]
	v_lshl_add_u64 v[20:21], v[6:7], 0, v[20:21]
	v_lshl_add_u64 v[22:23], v[6:7], 0, v[8:9]
	v_lshl_add_u64 v[24:25], v[6:7], 0, v[10:11]
	v_lshl_add_u64 v[26:27], v[6:7], 0, v[12:13]
	v_lshl_add_u64 v[28:29], v[6:7], 0, v[14:15]
	v_lshl_add_u64 v[30:31], v[6:7], 0, v[16:17]
	v_lshl_add_u64 v[32:33], v[6:7], 0, v[18:19]
	global_load_dwordx4 v[2:5], v[4:5], off nt
	s_nop 0
	global_load_dwordx4 v[6:9], v[20:21], off nt
	global_load_dwordx4 v[10:13], v[22:23], off nt
	global_load_dwordx4 v[14:17], v[24:25], off nt
	s_nop 0
	global_load_dwordx4 v[18:21], v[26:27], off nt
	global_load_dwordx4 v[22:25], v[28:29], off nt
	s_nop 0
	global_load_dwordx4 v[26:29], v[30:31], off nt
	s_nop 0
	global_load_dwordx4 v[30:33], v[32:33], off nt
	v_add_u32_e32 v48, s80, v55
	v_add_u32_e32 v41, 0x2020, v53
	v_add_u32_e32 v42, 0x2028, v53
	v_add_u32_e32 v44, 0x4040, v53
	v_add_u32_e32 v46, 0x4048, v53
	v_add_u32_e32 v50, 0x6060, v53
	v_add_u32_e32 v51, 0x6068, v53
	v_add_u32_e32 v52, 0x8080, v53
	v_add_u32_e32 v54, 0x8088, v53
	v_add_u32_e32 v56, 0xa0a0, v53
	v_add_u32_e32 v58, 0xa0a8, v53
	v_add_u32_e32 v65, 0xc0c0, v53
	v_add_u32_e32 v66, 0xc0c8, v53
	v_add_u32_e32 v67, 0xe0e0, v53
	v_add_u32_e32 v68, 0xe0e8, v53
	v_ashrrev_i32_e32 v49, 31, v48
	v_lshlrev_b64 v[48:49], 11, v[48:49]
	s_ashr_i32 s93, s92, 31
	v_lshl_add_u64 v[48:49], s[90:91], 0, v[48:49]
	s_add_i32 s26, s26, s88
	s_add_i32 s39, s39, s5
	v_lshl_add_u64 v[48:49], s[92:93], 1, v[48:49]
	s_cmp_lt_i32 s26, 32
	v_lshl_add_u64 v[48:49], v[48:49], 0, v[34:35]
	s_waitcnt vmcnt(7)
	ds_write2_b32 v53, v2, v3 offset1:1
	ds_write2_b32 v53, v4, v5 offset0:2 offset1:3
	s_waitcnt vmcnt(6)
	ds_write2_b32 v41, v6, v7 offset1:1
	ds_write2_b32 v42, v8, v9 offset1:1
	s_waitcnt vmcnt(5)
	ds_write2_b32 v44, v10, v11 offset1:1
	ds_write2_b32 v46, v12, v13 offset1:1
	s_waitcnt vmcnt(4)
	ds_write2_b32 v50, v14, v15 offset1:1
	ds_write2_b32 v51, v16, v17 offset1:1
	s_waitcnt vmcnt(3)
	ds_write2_b32 v52, v18, v19 offset1:1
	ds_write2_b32 v54, v20, v21 offset1:1
	s_waitcnt vmcnt(2)
	ds_write2_b32 v56, v22, v23 offset1:1
	ds_write2_b32 v58, v24, v25 offset1:1
	s_waitcnt vmcnt(1)
	ds_write2_b32 v65, v26, v27 offset1:1
	ds_write2_b32 v66, v28, v29 offset1:1
	s_waitcnt vmcnt(0)
	ds_write2_b32 v67, v30, v31 offset1:1
	ds_write2_b32 v68, v32, v33 offset1:1
	s_waitcnt lgkmcnt(0)
	s_barrier
	ds_read_b32 v2, v57
	ds_read_b32 v3, v57 offset:1028
	ds_read_b32 v4, v57 offset:2056
	ds_read_b32 v5, v57 offset:3084
	ds_read_b32 v6, v57 offset:4112
	ds_read_b32 v7, v57 offset:5140
	ds_read_b32 v8, v57 offset:6168
	ds_read_b32 v9, v57 offset:7196
	ds_read_b32 v10, v57 offset:8224
	ds_read_b32 v11, v57 offset:9252
	ds_read_b32 v12, v57 offset:10280
	ds_read_b32 v13, v57 offset:11308
	ds_read_b32 v14, v57 offset:12336
	ds_read_b32 v15, v57 offset:13364
	ds_read_b32 v16, v57 offset:14392
	ds_read_b32 v17, v57 offset:15420
	ds_read_b32 v18, v57 offset:16448
	ds_read_b32 v19, v57 offset:17476
	ds_read_b32 v20, v57 offset:18504
	ds_read_b32 v21, v57 offset:19532
	ds_read_b32 v22, v57 offset:20560
	ds_read_b32 v23, v57 offset:21588
	ds_read_b32 v24, v57 offset:22616
	ds_read_b32 v25, v57 offset:23644
	ds_read_b32 v26, v57 offset:24672
	ds_read_b32 v27, v57 offset:25700
	ds_read_b32 v28, v57 offset:26728
	ds_read_b32 v29, v57 offset:27756
	ds_read_b32 v30, v57 offset:28784
	ds_read_b32 v31, v57 offset:29812
	ds_read_b32 v32, v57 offset:30840
	ds_read_b32 v33, v57 offset:31868
	s_waitcnt lgkmcnt(14)
	v_cvt_pk_bf16_f32 v2, v2, v3
	v_cvt_pk_bf16_f32 v3, v4, v5
	v_cvt_pk_bf16_f32 v4, v6, v7
	v_cvt_pk_bf16_f32 v5, v8, v9
	v_cvt_pk_bf16_f32 v6, v10, v11
	v_cvt_pk_bf16_f32 v7, v12, v13
	v_cvt_pk_bf16_f32 v8, v14, v15
	v_cvt_pk_bf16_f32 v9, v16, v17
	v_cvt_pk_bf16_f32 v10, v18, v19
	s_waitcnt lgkmcnt(12)
	v_cvt_pk_bf16_f32 v11, v20, v21
	s_waitcnt lgkmcnt(10)
	v_cvt_pk_bf16_f32 v12, v22, v23
	s_waitcnt lgkmcnt(8)
	v_cvt_pk_bf16_f32 v13, v24, v25
	s_waitcnt lgkmcnt(6)
	v_cvt_pk_bf16_f32 v14, v26, v27
	s_waitcnt lgkmcnt(4)
	v_cvt_pk_bf16_f32 v15, v28, v29
	s_waitcnt lgkmcnt(2)
	v_cvt_pk_bf16_f32 v16, v30, v31
	s_waitcnt lgkmcnt(0)
	v_cvt_pk_bf16_f32 v17, v32, v33
	global_store_dwordx4 v[48:49], v[2:5], off
	global_store_dwordx4 v[48:49], v[6:9], off offset:16
	global_store_dwordx4 v[48:49], v[10:13], off offset:32
	global_store_dwordx4 v[48:49], v[14:17], off offset:48
	s_barrier
	s_cbranch_scc1 .LBB0_61

; __device__ __forceinline__ void convT_tile(const float* src, int ldsrc, const float* sc, bf16_t* dst, int dstld, int k0, int n0, int swiglu, LAS float* t) {
;     ...
;     { const int r = tid >> 6, c4 = (tid & 63) * 4;
;       int ncol = n0 + c4; if (swiglu) { const int blk = n0 >> 8; ncol = (c4 < 128) ? (128 * blk + c4) : (FF + 128 * blk + (c4 - 128)); }
;       f32x4 v[8]; float sv[8];
; #pragma unroll
;       for (int i = 0; i < 8; ++i) { const int rr = r + 8 * i; v[i] = *(const f32x4*)(src + (size_t)(k0 + rr) * ldsrc + ncol); sv[i] = sc ? sc[k0 + rr] : 1.0f; }
.LBB0_70:
	s_ashr_i32 s0, s26, 31
	s_lshr_b32 s0, s0, 28
	s_add_i32 s0, s26, s0
	s_ashr_i32 s80, s0, 4
	s_lshl_b32 s0, s80, 7
	v_or_b32_e32 v2, s0, v45
	v_add_u32_e32 v3, s0, v47
	s_lshl_b32 s81, s80, 10
	v_cndmask_b32_e64 v2, v3, v2, s[6:7]
	s_sub_i32 s0, s39, s81
	v_ashrrev_i32_e32 v3, 31, v2
	v_add_u32_e32 v30, s0, v37
	v_lshl_add_u64 v[32:33], v[2:3], 2, s[46:47]
	v_mad_i64_i32 v[2:3], s[0:1], v30, s24, v[32:33]
	global_load_dwordx4 v[2:5], v[2:3], off nt
	v_ashrrev_i32_e32 v31, 31, v30
	v_cndmask_b32_e64 v6, 0, 1, s[34:35]
	v_mov_b32_e32 v42, 1.0
	v_cmp_ne_u32_e64 s[0:1], 1, v6
	s_andn2_b64 vcc, exec, s[34:35]
	v_lshl_add_u64 v[50:51], v[30:31], 2, s[90:91]
	v_mov_b32_e32 v46, 1.0
	s_cbranch_vccnz .LBB0_72
	global_load_dword v46, v[50:51], off

; #define LAS __attribute__((address_space(3)))
; __device__ __forceinline__ unsigned cvt_pk_bf16(float lo, float hi) { const f32x2 v = {lo, hi}; return __builtin_bit_cast(unsigned, __builtin_convertvector(v, bfx2_t)); }
; __device__ __forceinline__ void convT_tile(const float* src, int ldsrc, const float* sc, bf16_t* dst, int dstld, int k0, int n0, int swiglu, LAS float* t) {
;     const int tid = threadIdx.x;
;     { const int r = tid >> 6, c4 = (tid & 63) * 4;
;       int ncol = n0 + c4; if (swiglu) { const int blk = n0 >> 8; ncol = (c4 < 128) ? (128 * blk + c4) : (FF + 128 * blk + (c4 - 128)); }
;       f32x4 v[8]; float sv[8];
; #pragma unroll
;       for (int i = 0; i < 8; ++i) { const int rr = r + 8 * i; v[i] = *(const f32x4*)(src + (size_t)(k0 + rr) * ldsrc + ncol); sv[i] = sc ? sc[k0 + rr] : 1.0f; }
; #pragma unroll
;       for (int i = 0; i < 8; ++i) { const int rr = r + 8 * i; t[rr * 257 + c4 + 0] = v[i][0] * sv[i]; t[rr * 257 + c4 + 1] = v[i][1] * sv[i]; t[rr * 257 + c4 + 2] = v[i][2] * sv[i]; t[rr * 257 + c4 + 3] = v[i][3] * sv[i]; } }
;     __syncthreads();
;     { const int nn = tid >> 1, kh = (tid & 1) * 32;
; #pragma unroll
;       for (int q = 0; q < 4; ++q) { float v[8];
; #pragma unroll
;           for (int j = 0; j < 8; ++j) v[j] = t[(kh + q * 8 + j) * 257 + nn];
;           u32x4 w; w.x = cvt_pk_bf16(v[0], v[1]); w.y = cvt_pk_bf16(v[2], v[3]); w.z = cvt_pk_bf16(v[4], v[5]); w.w = cvt_pk_bf16(v[6], v[7]);
;           *(u32x4*)(dst + (size_t)(n0 + nn) * dstld + k0 + kh + q * 8) = w; } }
;     __syncthreads();
; }
.LBB0_88:
	s_mul_hi_i32 s64, s26, 0x2e8ba2e9
	s_lshr_b32 s65, s64, 31
	s_ashr_i32 s64, s64, 3
	s_add_i32 s64, s64, s65
	s_mul_i32 s65, s64, 0xfffff500
	s_lshl_b32 s80, s64, 8
	s_add_i32 s64, s39, s65
	v_or_b32_e32 v2, s80, v45
	v_add_u32_e32 v4, s64, v37
	v_ashrrev_i32_e32 v3, 31, v2
	v_lshl_add_u64 v[6:7], v[2:3], 2, s[0:1]
	v_add_u32_e32 v2, 8, v4
	v_add_u32_e32 v8, 16, v4
	v_add_u32_e32 v10, 24, v4
	v_add_u32_e32 v12, 32, v4
	v_add_u32_e32 v14, 40, v4
	v_add_u32_e32 v16, 48, v4
	v_add_u32_e32 v18, 56, v4
	v_ashrrev_i32_e32 v5, 31, v4
	v_ashrrev_i32_e32 v3, 31, v2
	v_ashrrev_i32_e32 v9, 31, v8
	v_ashrrev_i32_e32 v11, 31, v10
	v_ashrrev_i32_e32 v13, 31, v12
	v_ashrrev_i32_e32 v15, 31, v14
	v_ashrrev_i32_e32 v17, 31, v16
	v_ashrrev_i32_e32 v19, 31, v18
	v_lshlrev_b64 v[4:5], 12, v[4:5]
	v_lshlrev_b64 v[20:21], 12, v[2:3]
	v_lshlrev_b64 v[8:9], 12, v[8:9]
	v_lshlrev_b64 v[10:11], 12, v[10:11]
	v_lshlrev_b64 v[12:13], 12, v[12:13]
	v_lshlrev_b64 v[14:15], 12, v[14:15]
	v_lshlrev_b64 v[16:17], 12, v[16:17]
	v_lshlrev_b64 v[18:19], 12, v[18:19]
	v_lshl_add_u64 v[4:5], v[6:7], 0, v[4:5]
	v_lshl_add_u64 v[20:21], v[6:7], 0, v[20:21]
	v_lshl_add_u64 v[22:23], v[6:7], 0, v[8:9]
	v_lshl_add_u64 v[24:25], v[6:7], 0, v[10:11]
	v_lshl_add_u64 v[26:27], v[6:7], 0, v[12:13]
	v_lshl_add_u64 v[28:29], v[6:7], 0, v[14:15]
	v_lshl_add_u64 v[30:31], v[6:7], 0, v[16:17]
	v_lshl_add_u64 v[32:33], v[6:7], 0, v[18:19]
	global_load_dwordx4 v[2:5], v[4:5], off nt
	s_nop 0
	global_load_dwordx4 v[6:9], v[20:21], off nt
	global_load_dwordx4 v[10:13], v[22:23], off nt
	global_load_dwordx4 v[14:17], v[24:25], off nt
	s_nop 0
	global_load_dwordx4 v[18:21], v[26:27], off nt
	global_load_dwordx4 v[22:25], v[28:29], off nt
	s_nop 0
	global_load_dwordx4 v[26:29], v[30:31], off nt
	s_nop 0
	global_load_dwordx4 v[30:33], v[32:33], off nt
	v_add_u32_e32 v41, 0x2020, v53
	v_add_u32_e32 v42, 0x2028, v53
	v_add_u32_e32 v44, 0x4040, v53
	v_add_u32_e32 v46, 0x4048, v53
	v_add_u32_e32 v50, 0x6060, v53
	v_add_u32_e32 v51, 0x6068, v53
	v_add_u32_e32 v52, 0x8080, v53
	v_add_u32_e32 v54, 0x8088, v53
	v_add_u32_e32 v56, 0xa0a0, v53
	v_add_u32_e32 v58, 0xa0a8, v53
	v_add_u32_e32 v65, 0xc0c0, v53
	v_add_u32_e32 v66, 0xc0c8, v53
	v_add_u32_e32 v67, 0xe0e0, v53
	v_add_u32_e32 v68, 0xe0e8, v53
	v_mov_b64_e32 v[48:49], s[46:47]
	v_add_u32_e32 v69, s80, v55
	v_mad_i64_i32 v[48:49], s[80:81], v69, s25, v[48:49]
	s_ashr_i32 s65, s64, 31
	s_add_i32 s26, s26, s88
	s_add_i32 s39, s39, s5
	v_lshl_add_u64 v[48:49], s[64:65], 1, v[48:49]
	s_cmpk_lt_i32 s26, 0xb0
	v_lshl_add_u64 v[48:49], v[48:49], 0, v[34:35]
	s_waitcnt vmcnt(7)
	ds_write2_b32 v53, v2, v3 offset1:1
	ds_write2_b32 v53, v4, v5 offset0:2 offset1:3
	s_waitcnt vmcnt(6)
	ds_write2_b32 v41, v6, v7 offset1:1
	ds_write2_b32 v42, v8, v9 offset1:1
	s_waitcnt vmcnt(5)
	ds_write2_b32 v44, v10, v11 offset1:1
	ds_write2_b32 v46, v12, v13 offset1:1
	s_waitcnt vmcnt(4)
	ds_write2_b32 v50, v14, v15 offset1:1
	ds_write2_b32 v51, v16, v17 offset1:1
	s_waitcnt vmcnt(3)
	ds_write2_b32 v52, v18, v19 offset1:1
	ds_write2_b32 v54, v20, v21 offset1:1
	s_waitcnt vmcnt(2)
	ds_write2_b32 v56, v22, v23 offset1:1
	ds_write2_b32 v58, v24, v25 offset1:1
	s_waitcnt vmcnt(1)
	ds_write2_b32 v65, v26, v27 offset1:1
	ds_write2_b32 v66, v28, v29 offset1:1
	s_waitcnt vmcnt(0)
	ds_write2_b32 v67, v30, v31 offset1:1
	ds_write2_b32 v68, v32, v33 offset1:1
	s_waitcnt lgkmcnt(0)
	s_barrier
	ds_read_b32 v2, v57
	ds_read_b32 v3, v57 offset:1028
	ds_read_b32 v4, v57 offset:2056
	ds_read_b32 v5, v57 offset:3084
	ds_read_b32 v6, v57 offset:4112
	ds_read_b32 v7, v57 offset:5140
	ds_read_b32 v8, v57 offset:6168
	ds_read_b32 v9, v57 offset:7196
	ds_read_b32 v10, v57 offset:8224
	ds_read_b32 v11, v57 offset:9252
	ds_read_b32 v12, v57 offset:10280
	ds_read_b32 v13, v57 offset:11308
	ds_read_b32 v14, v57 offset:12336
	ds_read_b32 v15, v57 offset:13364
	ds_read_b32 v16, v57 offset:14392
	ds_read_b32 v17, v57 offset:15420
	ds_read_b32 v18, v57 offset:16448
	ds_read_b32 v19, v57 offset:17476
	ds_read_b32 v20, v57 offset:18504
	ds_read_b32 v21, v57 offset:19532
	ds_read_b32 v22, v57 offset:20560
	ds_read_b32 v23, v57 offset:21588
	ds_read_b32 v24, v57 offset:22616
	ds_read_b32 v25, v57 offset:23644
	ds_read_b32 v26, v57 offset:24672
	ds_read_b32 v27, v57 offset:25700
	ds_read_b32 v28, v57 offset:26728
	ds_read_b32 v29, v57 offset:27756
	ds_read_b32 v30, v57 offset:28784
	ds_read_b32 v31, v57 offset:29812
	ds_read_b32 v32, v57 offset:30840
	ds_read_b32 v33, v57 offset:31868
	s_waitcnt lgkmcnt(14)
	v_cvt_pk_bf16_f32 v2, v2, v3
	v_cvt_pk_bf16_f32 v3, v4, v5
	v_cvt_pk_bf16_f32 v4, v6, v7
	v_cvt_pk_bf16_f32 v5, v8, v9
	v_cvt_pk_bf16_f32 v6, v10, v11
	v_cvt_pk_bf16_f32 v7, v12, v13
	v_cvt_pk_bf16_f32 v8, v14, v15
	v_cvt_pk_bf16_f32 v9, v16, v17
	v_cvt_pk_bf16_f32 v10, v18, v19
	s_waitcnt lgkmcnt(12)
	v_cvt_pk_bf16_f32 v11, v20, v21
	s_waitcnt lgkmcnt(10)
	v_cvt_pk_bf16_f32 v12, v22, v23
	s_waitcnt lgkmcnt(8)
	v_cvt_pk_bf16_f32 v13, v24, v25
	s_waitcnt lgkmcnt(6)
	v_cvt_pk_bf16_f32 v14, v26, v27
	s_waitcnt lgkmcnt(4)
	v_cvt_pk_bf16_f32 v15, v28, v29
	s_waitcnt lgkmcnt(2)
	v_cvt_pk_bf16_f32 v16, v30, v31
	s_waitcnt lgkmcnt(0)
	v_cvt_pk_bf16_f32 v17, v32, v33
	global_store_dwordx4 v[48:49], v[2:5], off
	global_store_dwordx4 v[48:49], v[6:9], off offset:16
	global_store_dwordx4 v[48:49], v[10:13], off offset:32
	global_store_dwordx4 v[48:49], v[14:17], off offset:48
	s_barrier
	s_cbranch_scc1 .LBB0_88

; __device__ __forceinline__ void convT_tile(const float* src, int ldsrc, const float* sc, bf16_t* dst, int dstld, int k0, int n0, int swiglu, LAS float* t) {
;     ...
;     { const int r = tid >> 6, c4 = (tid & 63) * 4;
;       int ncol = n0 + c4; if (swiglu) { const int blk = n0 >> 8; ncol = (c4 < 128) ? (128 * blk + c4) : (FF + 128 * blk + (c4 - 128)); }
;       f32x4 v[8]; float sv[8];
; #pragma unroll
;       for (int i = 0; i < 8; ++i) { const int rr = r + 8 * i; v[i] = *(const f32x4*)(src + (size_t)(k0 + rr) * ldsrc + ncol); sv[i] = sc ? sc[k0 + rr] : 1.0f; }
.LBB0_92:
	s_ashr_i32 s0, s26, 31
	s_lshr_b32 s0, s0, 28
	s_add_i32 s0, s26, s0
	s_ashr_i32 s0, s0, 4
	s_lshl_b32 s81, s0, 10
	s_lshl_b32 s80, s0, 8
	s_sub_i32 s0, s39, s81
	v_or_b32_e32 v2, s80, v45
	v_add_u32_e32 v32, s0, v37
	v_ashrrev_i32_e32 v3, 31, v2
	v_ashrrev_i32_e32 v33, 31, v32
	v_lshl_add_u64 v[30:31], v[2:3], 2, s[46:47]
	v_lshlrev_b64 v[2:3], 12, v[32:33]
	v_lshl_add_u64 v[2:3], v[30:31], 0, v[2:3]
	global_load_dwordx4 v[2:5], v[2:3], off nt
	v_cndmask_b32_e64 v6, 0, 1, s[36:37]
	v_mov_b32_e32 v42, 1.0
	v_cmp_ne_u32_e64 s[0:1], 1, v6
	s_andn2_b64 vcc, exec, s[36:37]
	v_lshl_add_u64 v[48:49], v[32:33], 2, s[42:43]
	v_mov_b32_e32 v44, 1.0
	s_cbranch_vccnz .LBB0_94
	global_load_dword v44, v[48:49], off

; __device__ __forceinline__ unsigned cvt_pk_bf16(float lo, float hi) { const f32x2 v = {lo, hi}; return __builtin_bit_cast(unsigned, __builtin_convertvector(v, bfx2_t)); }
; __device__ __forceinline__ void convT_tile(const float* src, int ldsrc, const float* sc, bf16_t* dst, int dstld, int k0, int n0, int swiglu, LAS float* t) {
;     ...
;     { const int r = tid >> 6, c4 = (tid & 63) * 4;
;       int ncol = n0 + c4; if (swiglu) { const int blk = n0 >> 8; ncol = (c4 < 128) ? (128 * blk + c4) : (FF + 128 * blk + (c4 - 128)); }
;       f32x4 v[8]; float sv[8];
; #pragma unroll
;       for (int i = 0; i < 8; ++i) { const int rr = r + 8 * i; v[i] = *(const f32x4*)(src + (size_t)(k0 + rr) * ldsrc + ncol); sv[i] = sc ? sc[k0 + rr] : 1.0f; }
; #pragma unroll
;       for (int i = 0; i < 8; ++i) { const int rr = r + 8 * i; t[rr * 257 + c4 + 0] = v[i][0] * sv[i]; t[rr * 257 + c4 + 1] = v[i][1] * sv[i]; t[rr * 257 + c4 + 2] = v[i][2] * sv[i]; t[rr * 257 + c4 + 3] = v[i][3] * sv[i]; } }
;     __syncthreads();
;     { const int nn = tid >> 1, kh = (tid & 1) * 32;
; #pragma unroll
;       for (int q = 0; q < 4; ++q) { float v[8];
; #pragma unroll
;           for (int j = 0; j < 8; ++j) v[j] = t[(kh + q * 8 + j) * 257 + nn];
;           u32x4 w; w.x = cvt_pk_bf16(v[0], v[1]); w.y = cvt_pk_bf16(v[2], v[3]); w.z = cvt_pk_bf16(v[4], v[5]); w.w = cvt_pk_bf16(v[6], v[7]);
;           *(u32x4*)(dst + (size_t)(n0 + nn) * dstld + k0 + kh + q * 8) = w; } }
.LBB0_110:
	s_ashr_i32 s42, s26, 31
	s_lshr_b32 s42, s42, 30
	s_add_i32 s42, s26, s42
	s_lshl_b32 s42, s42, 6
	s_and_b32 s43, s42, 0xffffff00
	s_sub_i32 s42, s39, s43
	v_or_b32_e32 v2, s43, v45
	v_add_u32_e32 v4, s42, v37
	v_ashrrev_i32_e32 v3, 31, v2
	v_lshl_add_u64 v[6:7], v[2:3], 2, s[0:1]
	v_add_u32_e32 v2, 8, v4
	v_add_u32_e32 v8, 16, v4
	v_add_u32_e32 v10, 24, v4
	v_add_u32_e32 v12, 32, v4
	v_add_u32_e32 v14, 40, v4
	v_add_u32_e32 v16, 48, v4
	v_add_u32_e32 v18, 56, v4
	v_ashrrev_i32_e32 v5, 31, v4
	v_ashrrev_i32_e32 v3, 31, v2
	v_ashrrev_i32_e32 v9, 31, v8
	v_ashrrev_i32_e32 v11, 31, v10
	v_ashrrev_i32_e32 v13, 31, v12
	v_ashrrev_i32_e32 v15, 31, v14
	v_ashrrev_i32_e32 v17, 31, v16
	v_ashrrev_i32_e32 v19, 31, v18
	v_lshlrev_b64 v[4:5], 12, v[4:5]
	v_lshlrev_b64 v[20:21], 12, v[2:3]
	v_lshlrev_b64 v[8:9], 12, v[8:9]
	v_lshlrev_b64 v[10:11], 12, v[10:11]
	v_lshlrev_b64 v[12:13], 12, v[12:13]
	v_lshlrev_b64 v[14:15], 12, v[14:15]
	v_lshlrev_b64 v[16:17], 12, v[16:17]
	v_lshlrev_b64 v[18:19], 12, v[18:19]
	v_lshl_add_u64 v[4:5], v[6:7], 0, v[4:5]
	v_lshl_add_u64 v[20:21], v[6:7], 0, v[20:21]
	v_lshl_add_u64 v[22:23], v[6:7], 0, v[8:9]
	v_lshl_add_u64 v[24:25], v[6:7], 0, v[10:11]
	v_lshl_add_u64 v[26:27], v[6:7], 0, v[12:13]
	v_lshl_add_u64 v[28:29], v[6:7], 0, v[14:15]
	v_lshl_add_u64 v[30:31], v[6:7], 0, v[16:17]
	v_lshl_add_u64 v[32:33], v[6:7], 0, v[18:19]
	global_load_dwordx4 v[2:5], v[4:5], off nt
	s_nop 0
	global_load_dwordx4 v[6:9], v[20:21], off nt
	global_load_dwordx4 v[10:13], v[22:23], off nt
	global_load_dwordx4 v[14:17], v[24:25], off nt
	s_nop 0
	global_load_dwordx4 v[18:21], v[26:27], off nt
	global_load_dwordx4 v[22:25], v[28:29], off nt
	s_nop 0
	global_load_dwordx4 v[26:29], v[30:31], off nt
	s_nop 0
	global_load_dwordx4 v[30:33], v[32:33], off nt
	v_add_u32_e32 v48, s43, v55
	v_add_u32_e32 v41, 0x2020, v53
	v_add_u32_e32 v42, 0x2028, v53
	v_add_u32_e32 v44, 0x4040, v53
	v_add_u32_e32 v46, 0x4048, v53
	v_add_u32_e32 v50, 0x6060, v53
	v_add_u32_e32 v51, 0x6068, v53
	v_add_u32_e32 v52, 0x8080, v53
	v_add_u32_e32 v54, 0x8088, v53
	v_add_u32_e32 v56, 0xa0a0, v53
	v_add_u32_e32 v58, 0xa0a8, v53
	v_add_u32_e32 v65, 0xc0c0, v53
	v_add_u32_e32 v66, 0xc0c8, v53
	v_add_u32_e32 v67, 0xe0e0, v53
	v_add_u32_e32 v68, 0xe0e8, v53
	v_ashrrev_i32_e32 v49, 31, v48
	v_lshlrev_b64 v[48:49], 9, v[48:49]
	s_ashr_i32 s43, s42, 31
	v_lshl_add_u64 v[48:49], s[40:41], 0, v[48:49]
	s_add_i32 s26, s26, s88
	s_add_i32 s39, s39, s5
	v_lshl_add_u64 v[48:49], s[42:43], 1, v[48:49]
	s_cmp_lt_i32 s26, 16
	v_lshl_add_u64 v[48:49], v[48:49], 0, v[34:35]
	s_waitcnt vmcnt(7)
	ds_write2_b32 v53, v2, v3 offset1:1
	ds_write2_b32 v53, v4, v5 offset0:2 offset1:3
	s_waitcnt vmcnt(6)
	ds_write2_b32 v41, v6, v7 offset1:1
	ds_write2_b32 v42, v8, v9 offset1:1
	s_waitcnt vmcnt(5)
	ds_write2_b32 v44, v10, v11 offset1:1
	ds_write2_b32 v46, v12, v13 offset1:1
	s_waitcnt vmcnt(4)
	ds_write2_b32 v50, v14, v15 offset1:1
	ds_write2_b32 v51, v16, v17 offset1:1
	s_waitcnt vmcnt(3)
	ds_write2_b32 v52, v18, v19 offset1:1
	ds_write2_b32 v54, v20, v21 offset1:1
	s_waitcnt vmcnt(2)
	ds_write2_b32 v56, v22, v23 offset1:1
	ds_write2_b32 v58, v24, v25 offset1:1
	s_waitcnt vmcnt(1)
	ds_write2_b32 v65, v26, v27 offset1:1
	ds_write2_b32 v66, v28, v29 offset1:1
	s_waitcnt vmcnt(0)
	ds_write2_b32 v67, v30, v31 offset1:1
	ds_write2_b32 v68, v32, v33 offset1:1
	s_waitcnt lgkmcnt(0)
	s_barrier
	ds_read_b32 v2, v57
	ds_read_b32 v3, v57 offset:1028
	ds_read_b32 v4, v57 offset:2056
	ds_read_b32 v5, v57 offset:3084
	ds_read_b32 v6, v57 offset:4112
	ds_read_b32 v7, v57 offset:5140
	ds_read_b32 v8, v57 offset:6168
	ds_read_b32 v9, v57 offset:7196
	ds_read_b32 v10, v57 offset:8224
	ds_read_b32 v11, v57 offset:9252
	ds_read_b32 v12, v57 offset:10280
	ds_read_b32 v13, v57 offset:11308
	ds_read_b32 v14, v57 offset:12336
	ds_read_b32 v15, v57 offset:13364
	ds_read_b32 v16, v57 offset:14392
	ds_read_b32 v17, v57 offset:15420
	ds_read_b32 v18, v57 offset:16448
	ds_read_b32 v19, v57 offset:17476
	ds_read_b32 v20, v57 offset:18504
	ds_read_b32 v21, v57 offset:19532
	ds_read_b32 v22, v57 offset:20560
	ds_read_b32 v23, v57 offset:21588
	ds_read_b32 v24, v57 offset:22616
	ds_read_b32 v25, v57 offset:23644
	ds_read_b32 v26, v57 offset:24672
	ds_read_b32 v27, v57 offset:25700
	ds_read_b32 v28, v57 offset:26728
	ds_read_b32 v29, v57 offset:27756
	ds_read_b32 v30, v57 offset:28784
	ds_read_b32 v31, v57 offset:29812
	ds_read_b32 v32, v57 offset:30840
	ds_read_b32 v33, v57 offset:31868
	s_waitcnt lgkmcnt(14)
	v_cvt_pk_bf16_f32 v2, v2, v3
	v_cvt_pk_bf16_f32 v3, v4, v5
	v_cvt_pk_bf16_f32 v4, v6, v7
	v_cvt_pk_bf16_f32 v5, v8, v9
	v_cvt_pk_bf16_f32 v6, v10, v11
	v_cvt_pk_bf16_f32 v7, v12, v13
	v_cvt_pk_bf16_f32 v8, v14, v15
	v_cvt_pk_bf16_f32 v9, v16, v17
	v_cvt_pk_bf16_f32 v10, v18, v19
	s_waitcnt lgkmcnt(12)
	v_cvt_pk_bf16_f32 v11, v20, v21
	s_waitcnt lgkmcnt(10)
	v_cvt_pk_bf16_f32 v12, v22, v23
	s_waitcnt lgkmcnt(8)
	v_cvt_pk_bf16_f32 v13, v24, v25
	s_waitcnt lgkmcnt(6)
	v_cvt_pk_bf16_f32 v14, v26, v27
	s_waitcnt lgkmcnt(4)
	v_cvt_pk_bf16_f32 v15, v28, v29
	s_waitcnt lgkmcnt(2)
	v_cvt_pk_bf16_f32 v16, v30, v31
	s_waitcnt lgkmcnt(0)
	v_cvt_pk_bf16_f32 v17, v32, v33
	global_store_dwordx4 v[48:49], v[2:5], off
	global_store_dwordx4 v[48:49], v[6:9], off offset:16
	global_store_dwordx4 v[48:49], v[10:13], off offset:32
	global_store_dwordx4 v[48:49], v[14:17], off offset:48
	s_barrier
	s_cbranch_scc1 .LBB0_110
	s_branch .LBB0_14

; #define LAS __attribute__((address_space(3)))
; __device__ __forceinline__ unsigned cvt_pk_bf16(float lo, float hi) { const f32x2 v = {lo, hi}; return __builtin_bit_cast(unsigned, __builtin_convertvector(v, bfx2_t)); }
; __device__ __forceinline__ void conv_p(const Params& P, int l) {
;     ...
;         for (int q = 0; q < 4; ++q) { a[q] = *(const f32x4*)(src + (i + q * stride) * 8); b[q] = *(const f32x4*)(src + (i + q * stride) * 8 + 4); }
; #pragma unroll
;         for (int q = 0; q < 4; ++q) { u32x4 w; w.x = cvt_pk_bf16(a[q][0], a[q][1]); w.y = cvt_pk_bf16(a[q][2], a[q][3]); w.z = cvt_pk_bf16(b[q][0], b[q][1]); w.w = cvt_pk_bf16(b[q][2], b[q][3]);
;             *(u32x4*)(dst + (i + q * stride) * 8) = w; }
; template <int PASS> __device__ void ssm_pass(const Params& P, int l, LAS unsigned char* lds) {
;     ...
;             u32x2 unext = ucur; if (mt < 63) unext = *(const u32x2*)(zrow + (size_t)(mt + 1) * 16 * DM);
;             const bf16x4 af = __builtin_bit_cast(bf16x4, ucur);
;             f32x4 d[8];
; #pragma unroll
;             for (int t = 0; t < 8; ++t) d[t] = __builtin_amdgcn_mfma_f32_16x16x16bf16_1k(af, bf[t], (f32x4){0.f, 0.f, 0.f, 0.f}, 0, 0, 0);
; #pragma unroll
;             for (int tq = 0; tq < 4; ++tq)
; #pragma unroll
;                 for (int j = 0; j < 4; ++j) *(LAS f32x2*)(BU + (4 * fq + j) * 528 + (16 * tq + fr) * 8) = (f32x2){d[tq][j], d[tq + 4][j]};
;             asm volatile("s_waitcnt lgkmcnt(0)" ::: "memory");
; #pragma unroll
;             for (int j = 0; j < 16; ++j) {
;                 const f32x2 bu = *(const LAS f32x2*)(BU + j * 528 + lane * 8);
;                 sv = __builtin_elementwise_fma(ayn, __builtin_shufflevector(sv, sv, 1, 0), __builtin_elementwise_fma(axx, sv, bu));
.Lp1_loop:
	s_waitcnt vmcnt(9)
	ds_write_b64 v146, v[40:41]
	ds_read_b128 v[156:159], v196
	ds_read_b128 v[200:203], v197
	global_load_dwordx2 v[50:51], v[54:55], off
	v_lshl_add_u64 v[54:55], v[54:55], 0, s[20:21]
	global_load_dwordx4 v[60:63], v[56:57], off nt
	v_fma_f32 v70, v30, v34, v88
	v_fma_f32 v71, v30, v35, v104
	v_fma_f32 v72, v10, v35, v70
	v_fma_f32 v73, v11, v34, v71
	v_fma_f32 v70, v30, v72, v89
	v_fma_f32 v71, v30, v73, v105
	v_fma_f32 v34, v10, v73, v70
	v_fma_f32 v35, v11, v72, v71
	v_fma_f32 v70, v30, v34, v90
	v_fma_f32 v71, v30, v35, v106
	v_fma_f32 v72, v10, v35, v70
	v_fma_f32 v73, v11, v34, v71
	v_fma_f32 v70, v30, v72, v91
	v_fma_f32 v71, v30, v73, v107
	v_fma_f32 v34, v10, v73, v70
	v_fma_f32 v35, v11, v72, v71
	s_waitcnt lgkmcnt(0)
	v_mfma_f32_32x32x16_bf16 v[120:135], v[156:159], v[12:15], 0
	v_mfma_f32_32x32x16_bf16 v[226:241], v[156:159], v[20:23], 0
	v_fma_f32 v70, v30, v34, v92
	v_fma_f32 v71, v30, v35, v108
	v_fma_f32 v72, v10, v35, v70
	v_fma_f32 v73, v11, v34, v71
	v_fma_f32 v70, v30, v72, v93
	v_fma_f32 v71, v30, v73, v109
	v_fma_f32 v34, v10, v73, v70
	v_fma_f32 v35, v11, v72, v71
	v_fma_f32 v70, v30, v34, v94
	v_fma_f32 v71, v30, v35, v110
	v_fma_f32 v72, v10, v35, v70
	v_fma_f32 v73, v11, v34, v71
	v_fma_f32 v70, v30, v72, v95
	v_fma_f32 v71, v30, v73, v111
	v_fma_f32 v34, v10, v73, v70
	v_fma_f32 v35, v11, v72, v71
	v_mfma_f32_32x32x16_bf16 v[120:135], v[200:203], v[16:19], v[120:135]
	v_mfma_f32_32x32x16_bf16 v[226:241], v[200:203], v[24:27], v[226:241]
	v_fma_f32 v70, v30, v34, v96
	v_fma_f32 v71, v30, v35, v112
	v_fma_f32 v72, v10, v35, v70
	v_fma_f32 v73, v11, v34, v71
	v_fma_f32 v70, v30, v72, v97
	v_fma_f32 v71, v30, v73, v113
	v_fma_f32 v34, v10, v73, v70
	v_fma_f32 v35, v11, v72, v71
	v_fma_f32 v70, v30, v34, v98
	v_fma_f32 v71, v30, v35, v114
	v_fma_f32 v72, v10, v35, v70
	v_fma_f32 v73, v11, v34, v71
	v_fma_f32 v70, v30, v72, v99
	v_fma_f32 v71, v30, v73, v115
	v_fma_f32 v34, v10, v73, v70
	v_fma_f32 v35, v11, v72, v71
	v_fma_f32 v70, v30, v34, v100
	v_fma_f32 v71, v30, v35, v116
	v_fma_f32 v72, v10, v35, v70
	v_fma_f32 v73, v11, v34, v71
	v_fma_f32 v70, v30, v72, v101
	v_fma_f32 v71, v30, v73, v117
	v_fma_f32 v34, v10, v73, v70
	v_fma_f32 v35, v11, v72, v71
	v_fma_f32 v70, v30, v34, v102
	v_fma_f32 v71, v30, v35, v118
	v_fma_f32 v72, v10, v35, v70
	v_fma_f32 v73, v11, v34, v71
	v_fma_f32 v70, v30, v72, v103
	v_fma_f32 v71, v30, v73, v119
	v_fma_f32 v34, v10, v73, v70
	v_fma_f32 v35, v11, v72, v71
	s_waitcnt vmcnt(9)
	ds_write_b64 v146, v[42:43]
	ds_read_b128 v[156:159], v196
	ds_read_b128 v[200:203], v197
	global_load_dwordx2 v[52:53], v[54:55], off
	v_lshl_add_u64 v[54:55], v[54:55], 0, s[20:21]
	global_load_dwordx4 v[64:67], v[56:57], off offset:16 nt
	s_mov_b64 s[22:23], 0x400000
	v_lshl_add_u64 v[56:57], v[56:57], 0, s[22:23]
	v_fma_f32 v70, v30, v34, v120
	v_fma_f32 v71, v30, v35, v226
	v_fma_f32 v72, v10, v35, v70
	v_fma_f32 v73, v11, v34, v71
	v_fma_f32 v70, v30, v72, v121
	v_fma_f32 v71, v30, v73, v227
	v_fma_f32 v34, v10, v73, v70
	v_fma_f32 v35, v11, v72, v71
	v_fma_f32 v70, v30, v34, v122
	v_fma_f32 v71, v30, v35, v228
	v_fma_f32 v72, v10, v35, v70
	v_fma_f32 v73, v11, v34, v71
	v_fma_f32 v70, v30, v72, v123
	v_fma_f32 v71, v30, v73, v229
	v_fma_f32 v34, v10, v73, v70
	v_fma_f32 v35, v11, v72, v71
	s_waitcnt lgkmcnt(0)
; #define LAS __attribute__((address_space(3)))
; __device__ __forceinline__ unsigned cvt_pk_bf16(float lo, float hi) { const f32x2 v = {lo, hi}; return __builtin_bit_cast(unsigned, __builtin_convertvector(v, bfx2_t)); }
; __device__ __forceinline__ void conv_p(const Params& P, int l) {
;     ...
;         for (int q = 0; q < 4; ++q) { u32x4 w; w.x = cvt_pk_bf16(a[q][0], a[q][1]); w.y = cvt_pk_bf16(a[q][2], a[q][3]); w.z = cvt_pk_bf16(b[q][0], b[q][1]); w.w = cvt_pk_bf16(b[q][2], b[q][3]);
;             *(u32x4*)(dst + (i + q * stride) * 8) = w; }
; template <int PASS> __device__ void ssm_pass(const Params& P, int l, LAS unsigned char* lds) {
;     ...
;             u32x2 unext = ucur; if (mt < 63) unext = *(const u32x2*)(zrow + (size_t)(mt + 1) * 16 * DM);
;             const bf16x4 af = __builtin_bit_cast(bf16x4, ucur);
;             f32x4 d[8];
; #pragma unroll
;             for (int t = 0; t < 8; ++t) d[t] = __builtin_amdgcn_mfma_f32_16x16x16bf16_1k(af, bf[t], (f32x4){0.f, 0.f, 0.f, 0.f}, 0, 0, 0);
; #pragma unroll
;             for (int tq = 0; tq < 4; ++tq)
; #pragma unroll
;                 for (int j = 0; j < 4; ++j) *(LAS f32x2*)(BU + (4 * fq + j) * 528 + (16 * tq + fr) * 8) = (f32x2){d[tq][j], d[tq + 4][j]};
;             asm volatile("s_waitcnt lgkmcnt(0)" ::: "memory");
; #pragma unroll
;             for (int j = 0; j < 16; ++j) {
;                 const f32x2 bu = *(const LAS f32x2*)(BU + j * 528 + lane * 8);
;                 sv = __builtin_elementwise_fma(ayn, __builtin_shufflevector(sv, sv, 1, 0), __builtin_elementwise_fma(axx, sv, bu));
	v_mfma_f32_32x32x16_bf16 v[88:103], v[156:159], v[12:15], 0
	v_mfma_f32_32x32x16_bf16 v[104:119], v[156:159], v[20:23], 0
	v_fma_f32 v70, v30, v34, v124
	v_fma_f32 v71, v30, v35, v230
	v_fma_f32 v72, v10, v35, v70
	v_fma_f32 v73, v11, v34, v71
	v_fma_f32 v70, v30, v72, v125
	v_fma_f32 v71, v30, v73, v231
	v_fma_f32 v34, v10, v73, v70
	v_fma_f32 v35, v11, v72, v71
	v_fma_f32 v70, v30, v34, v126
	v_fma_f32 v71, v30, v35, v232
	v_fma_f32 v72, v10, v35, v70
	v_fma_f32 v73, v11, v34, v71
	v_fma_f32 v70, v30, v72, v127
	v_fma_f32 v71, v30, v73, v233
	v_fma_f32 v34, v10, v73, v70
	v_fma_f32 v35, v11, v72, v71
	v_mfma_f32_32x32x16_bf16 v[88:103], v[200:203], v[16:19], v[88:103]
	v_mfma_f32_32x32x16_bf16 v[104:119], v[200:203], v[24:27], v[104:119]
	v_fma_f32 v70, v30, v34, v128
	v_fma_f32 v71, v30, v35, v234
	v_fma_f32 v72, v10, v35, v70
	v_fma_f32 v73, v11, v34, v71
	v_fma_f32 v70, v30, v72, v129
	v_fma_f32 v71, v30, v73, v235
	v_fma_f32 v34, v10, v73, v70
	v_fma_f32 v35, v11, v72, v71
	v_fma_f32 v70, v30, v34, v130
	v_fma_f32 v71, v30, v35, v236
	v_fma_f32 v72, v10, v35, v70
	v_fma_f32 v73, v11, v34, v71
	v_fma_f32 v70, v30, v72, v131
	v_fma_f32 v71, v30, v73, v237
	v_fma_f32 v34, v10, v73, v70
	v_fma_f32 v35, v11, v72, v71
	v_fma_f32 v70, v30, v34, v132
	v_fma_f32 v71, v30, v35, v238
	v_fma_f32 v72, v10, v35, v70
	v_fma_f32 v73, v11, v34, v71
	v_fma_f32 v70, v30, v72, v133
	v_fma_f32 v71, v30, v73, v239
	v_fma_f32 v34, v10, v73, v70
	v_fma_f32 v35, v11, v72, v71
	v_fma_f32 v70, v30, v34, v134
	v_fma_f32 v71, v30, v35, v240
	v_fma_f32 v72, v10, v35, v70
	v_fma_f32 v73, v11, v34, v71
	v_fma_f32 v70, v30, v72, v135
	v_fma_f32 v71, v30, v73, v241
	v_fma_f32 v34, v10, v73, v70
	v_fma_f32 v35, v11, v72, v71
	s_waitcnt vmcnt(9)
	ds_write_b64 v146, v[44:45]
	ds_read_b128 v[156:159], v196
	ds_read_b128 v[200:203], v197
	global_load_dwordx2 v[36:37], v[54:55], off
	v_lshl_add_u64 v[54:55], v[54:55], 0, s[20:21]
	global_load_dwordx2 v[144:145], v[54:55], off
	v_fma_f32 v70, v30, v34, v88
	v_fma_f32 v71, v30, v35, v104
	v_fma_f32 v72, v10, v35, v70
	v_fma_f32 v73, v11, v34, v71
	v_fma_f32 v70, v30, v72, v89
	v_fma_f32 v71, v30, v73, v105
	v_fma_f32 v34, v10, v73, v70
	v_fma_f32 v35, v11, v72, v71
	v_fma_f32 v70, v30, v34, v90
	v_fma_f32 v71, v30, v35, v106
	v_fma_f32 v72, v10, v35, v70
	v_fma_f32 v73, v11, v34, v71
	v_fma_f32 v70, v30, v72, v91
	v_fma_f32 v71, v30, v73, v107
	v_fma_f32 v34, v10, v73, v70
	v_fma_f32 v35, v11, v72, v71
	s_waitcnt lgkmcnt(0)
	v_mfma_f32_32x32x16_bf16 v[120:135], v[156:159], v[12:15], 0
	v_mfma_f32_32x32x16_bf16 v[226:241], v[156:159], v[20:23], 0
	v_fma_f32 v70, v30, v34, v92
	v_fma_f32 v71, v30, v35, v108
	v_fma_f32 v72, v10, v35, v70
	v_fma_f32 v73, v11, v34, v71
	v_fma_f32 v70, v30, v72, v93
	v_fma_f32 v71, v30, v73, v109
	v_fma_f32 v34, v10, v73, v70
	v_fma_f32 v35, v11, v72, v71
	v_fma_f32 v70, v30, v34, v94
	v_fma_f32 v71, v30, v35, v110
	v_fma_f32 v72, v10, v35, v70
	v_fma_f32 v73, v11, v34, v71
	v_fma_f32 v70, v30, v72, v95
	v_fma_f32 v71, v30, v73, v111
	v_fma_f32 v34, v10, v73, v70
	v_fma_f32 v35, v11, v72, v71
	v_mfma_f32_32x32x16_bf16 v[120:135], v[200:203], v[16:19], v[120:135]
	v_mfma_f32_32x32x16_bf16 v[226:241], v[200:203], v[24:27], v[226:241]
	v_fma_f32 v70, v30, v34, v96
	v_fma_f32 v71, v30, v35, v112
	v_fma_f32 v72, v10, v35, v70
	v_fma_f32 v73, v11, v34, v71
	v_fma_f32 v70, v30, v72, v97
	v_fma_f32 v71, v30, v73, v113
	v_fma_f32 v34, v10, v73, v70
	v_fma_f32 v35, v11, v72, v71
	v_fma_f32 v70, v30, v34, v98
	v_fma_f32 v71, v30, v35, v114
	v_fma_f32 v72, v10, v35, v70
	v_fma_f32 v73, v11, v34, v71
	v_fma_f32 v70, v30, v72, v99
	v_fma_f32 v71, v30, v73, v115
	v_fma_f32 v34, v10, v73, v70
	v_fma_f32 v35, v11, v72, v71
	v_fma_f32 v70, v30, v34, v100
	v_fma_f32 v71, v30, v35, v116
	v_fma_f32 v72, v10, v35, v70
	v_fma_f32 v73, v11, v34, v71
	v_fma_f32 v70, v30, v72, v101
	v_fma_f32 v71, v30, v73, v117
	v_fma_f32 v34, v10, v73, v70
	v_fma_f32 v35, v11, v72, v71
	v_fma_f32 v70, v30, v34, v102
	v_fma_f32 v71, v30, v35, v118
	v_fma_f32 v72, v10, v35, v70
	v_fma_f32 v73, v11, v34, v71
	v_fma_f32 v70, v30, v72, v103
	v_fma_f32 v71, v30, v73, v119
	v_fma_f32 v34, v10, v73, v70
	v_fma_f32 v35, v11, v72, v71
	s_waitcnt vmcnt(9)
	ds_write_b64 v146, v[46:47]
	ds_read_b128 v[156:159], v196
	ds_read_b128 v[200:203], v197
	global_load_dwordx2 v[40:41], v[54:55], off
	v_lshl_add_u64 v[54:55], v[54:55], 0, s[20:21]
	s_cmp_eq_u32 s12, 0
	s_cbranch_scc1 .Lp1_skip
	v_cvt_pk_bf16_f32 v82, v74, v75
	v_cvt_pk_bf16_f32 v83, v76, v77
	v_cvt_pk_bf16_f32 v84, v78, v79
	v_cvt_pk_bf16_f32 v85, v80, v81
	global_store_dwordx4 v[58:59], v[82:85], off
	s_mov_b64 s[22:23], 0x200000
	v_lshl_add_u64 v[58:59], v[58:59], 0, s[22:23]
	s_branch .Lp1_join

; #define LAS __attribute__((address_space(3)))
; __device__ __forceinline__ unsigned cvt_pk_bf16(float lo, float hi) { const f32x2 v = {lo, hi}; return __builtin_bit_cast(unsigned, __builtin_convertvector(v, bfx2_t)); }
; __device__ __forceinline__ void conv_p(const Params& P, int l) {
;     ...
;         for (int q = 0; q < 4; ++q) { a[q] = *(const f32x4*)(src + (i + q * stride) * 8); b[q] = *(const f32x4*)(src + (i + q * stride) * 8 + 4); }
; #pragma unroll
;         for (int q = 0; q < 4; ++q) { u32x4 w; w.x = cvt_pk_bf16(a[q][0], a[q][1]); w.y = cvt_pk_bf16(a[q][2], a[q][3]); w.z = cvt_pk_bf16(b[q][0], b[q][1]); w.w = cvt_pk_bf16(b[q][2], b[q][3]);
;             *(u32x4*)(dst + (i + q * stride) * 8) = w; }
; template <int PASS> __device__ void ssm_pass(const Params& P, int l, LAS unsigned char* lds) {
;     ...
;             u32x2 unext = ucur; if (mt < 63) unext = *(const u32x2*)(zrow + (size_t)(mt + 1) * 16 * DM);
;             const bf16x4 af = __builtin_bit_cast(bf16x4, ucur);
;             f32x4 d[8];
; #pragma unroll
;             for (int t = 0; t < 8; ++t) d[t] = __builtin_amdgcn_mfma_f32_16x16x16bf16_1k(af, bf[t], (f32x4){0.f, 0.f, 0.f, 0.f}, 0, 0, 0);
; #pragma unroll
;             for (int tq = 0; tq < 4; ++tq)
; #pragma unroll
;                 for (int j = 0; j < 4; ++j) *(LAS f32x2*)(BU + (4 * fq + j) * 528 + (16 * tq + fr) * 8) = (f32x2){d[tq][j], d[tq + 4][j]};
;             asm volatile("s_waitcnt lgkmcnt(0)" ::: "memory");
; #pragma unroll
;             for (int j = 0; j < 16; ++j) {
;                 const f32x2 bu = *(const LAS f32x2*)(BU + j * 528 + lane * 8);
;                 sv = __builtin_elementwise_fma(ayn, __builtin_shufflevector(sv, sv, 1, 0), __builtin_elementwise_fma(axx, sv, bu));
.Lp1_join:
	v_fma_f32 v70, v30, v34, v120
	v_fma_f32 v71, v30, v35, v226
	v_fma_f32 v72, v10, v35, v70
	v_fma_f32 v73, v11, v34, v71
	v_fma_f32 v70, v30, v72, v121
	v_fma_f32 v71, v30, v73, v227
	v_fma_f32 v34, v10, v73, v70
	v_fma_f32 v35, v11, v72, v71
	v_fma_f32 v70, v30, v34, v122
	v_fma_f32 v71, v30, v35, v228
	v_fma_f32 v72, v10, v35, v70
	v_fma_f32 v73, v11, v34, v71
	v_fma_f32 v70, v30, v72, v123
	v_fma_f32 v71, v30, v73, v229
	v_fma_f32 v34, v10, v73, v70
	v_fma_f32 v35, v11, v72, v71
	s_waitcnt lgkmcnt(0)
	v_mfma_f32_32x32x16_bf16 v[88:103], v[156:159], v[12:15], 0
	v_mfma_f32_32x32x16_bf16 v[104:119], v[156:159], v[20:23], 0
	v_fma_f32 v70, v30, v34, v124
	v_fma_f32 v71, v30, v35, v230
	v_fma_f32 v72, v10, v35, v70
	v_fma_f32 v73, v11, v34, v71
	v_fma_f32 v70, v30, v72, v125
	v_fma_f32 v71, v30, v73, v231
	v_fma_f32 v34, v10, v73, v70
	v_fma_f32 v35, v11, v72, v71
	v_fma_f32 v70, v30, v34, v126
	v_fma_f32 v71, v30, v35, v232
	v_fma_f32 v72, v10, v35, v70
	v_fma_f32 v73, v11, v34, v71
	v_fma_f32 v70, v30, v72, v127
	v_fma_f32 v71, v30, v73, v233
	v_fma_f32 v34, v10, v73, v70
	v_fma_f32 v35, v11, v72, v71
	v_mfma_f32_32x32x16_bf16 v[88:103], v[200:203], v[16:19], v[88:103]
	v_mfma_f32_32x32x16_bf16 v[104:119], v[200:203], v[24:27], v[104:119]
	v_fma_f32 v70, v30, v34, v128
	v_fma_f32 v71, v30, v35, v234
	v_fma_f32 v72, v10, v35, v70
	v_fma_f32 v73, v11, v34, v71
	v_fma_f32 v70, v30, v72, v129
	v_fma_f32 v71, v30, v73, v235
	v_fma_f32 v34, v10, v73, v70
	v_fma_f32 v35, v11, v72, v71
	v_fma_f32 v70, v30, v34, v130
	v_fma_f32 v71, v30, v35, v236
	v_fma_f32 v72, v10, v35, v70
	v_fma_f32 v73, v11, v34, v71
	v_fma_f32 v70, v30, v72, v131
	v_fma_f32 v71, v30, v73, v237
	v_fma_f32 v34, v10, v73, v70
	v_fma_f32 v35, v11, v72, v71
	v_fma_f32 v70, v30, v34, v132
	v_fma_f32 v71, v30, v35, v238
	v_fma_f32 v72, v10, v35, v70
	v_fma_f32 v73, v11, v34, v71
	v_fma_f32 v70, v30, v72, v133
	v_fma_f32 v71, v30, v73, v239
	v_fma_f32 v34, v10, v73, v70
	v_fma_f32 v35, v11, v72, v71
	v_fma_f32 v70, v30, v34, v134
	v_fma_f32 v71, v30, v35, v240
	v_fma_f32 v72, v10, v35, v70
	v_fma_f32 v73, v11, v34, v71
	v_fma_f32 v70, v30, v72, v135
	v_fma_f32 v71, v30, v73, v241
	v_fma_f32 v34, v10, v73, v70
	v_fma_f32 v35, v11, v72, v71
	s_waitcnt vmcnt(9)
	ds_write_b64 v146, v[48:49]
	ds_read_b128 v[156:159], v196
	ds_read_b128 v[200:203], v197
	global_load_dwordx2 v[42:43], v[54:55], off
	v_lshl_add_u64 v[54:55], v[54:55], 0, s[20:21]
	global_load_dwordx4 v[74:77], v[56:57], off nt
	v_fma_f32 v70, v30, v34, v88
	v_fma_f32 v71, v30, v35, v104
	v_fma_f32 v72, v10, v35, v70
	v_fma_f32 v73, v11, v34, v71
	v_fma_f32 v70, v30, v72, v89
	v_fma_f32 v71, v30, v73, v105
	v_fma_f32 v34, v10, v73, v70
	v_fma_f32 v35, v11, v72, v71
	v_fma_f32 v70, v30, v34, v90
	v_fma_f32 v71, v30, v35, v106
	v_fma_f32 v72, v10, v35, v70
	v_fma_f32 v73, v11, v34, v71
	v_fma_f32 v70, v30, v72, v91
	v_fma_f32 v71, v30, v73, v107
	v_fma_f32 v34, v10, v73, v70
	v_fma_f32 v35, v11, v72, v71
	s_waitcnt lgkmcnt(0)
	v_mfma_f32_32x32x16_bf16 v[120:135], v[156:159], v[12:15], 0
	v_mfma_f32_32x32x16_bf16 v[226:241], v[156:159], v[20:23], 0
	v_fma_f32 v70, v30, v34, v92
	v_fma_f32 v71, v30, v35, v108
	v_fma_f32 v72, v10, v35, v70
	v_fma_f32 v73, v11, v34, v71
	v_fma_f32 v70, v30, v72, v93
	v_fma_f32 v71, v30, v73, v109
	v_fma_f32 v34, v10, v73, v70
	v_fma_f32 v35, v11, v72, v71
	v_fma_f32 v70, v30, v34, v94
	v_fma_f32 v71, v30, v35, v110
	v_fma_f32 v72, v10, v35, v70
	v_fma_f32 v73, v11, v34, v71
	v_fma_f32 v70, v30, v72, v95
	v_fma_f32 v71, v30, v73, v111
	v_fma_f32 v34, v10, v73, v70
	v_fma_f32 v35, v11, v72, v71
	v_mfma_f32_32x32x16_bf16 v[120:135], v[200:203], v[16:19], v[120:135]
	v_mfma_f32_32x32x16_bf16 v[226:241], v[200:203], v[24:27], v[226:241]
	v_fma_f32 v70, v30, v34, v96
	v_fma_f32 v71, v30, v35, v112
	v_fma_f32 v72, v10, v35, v70
	v_fma_f32 v73, v11, v34, v71
	v_fma_f32 v70, v30, v72, v97
	v_fma_f32 v71, v30, v73, v113
	v_fma_f32 v34, v10, v73, v70
	v_fma_f32 v35, v11, v72, v71
	v_fma_f32 v70, v30, v34, v98
	v_fma_f32 v71, v30, v35, v114
	v_fma_f32 v72, v10, v35, v70
	v_fma_f32 v73, v11, v34, v71
	v_fma_f32 v70, v30, v72, v99
	v_fma_f32 v71, v30, v73, v115
	v_fma_f32 v34, v10, v73, v70
	v_fma_f32 v35, v11, v72, v71
	v_fma_f32 v70, v30, v34, v100
	v_fma_f32 v71, v30, v35, v116
	v_fma_f32 v72, v10, v35, v70
	v_fma_f32 v73, v11, v34, v71
	v_fma_f32 v70, v30, v72, v101
	v_fma_f32 v71, v30, v73, v117
	v_fma_f32 v34, v10, v73, v70
	v_fma_f32 v35, v11, v72, v71
	v_fma_f32 v70, v30, v34, v102
	v_fma_f32 v71, v30, v35, v118
	v_fma_f32 v72, v10, v35, v70
	v_fma_f32 v73, v11, v34, v71
	v_fma_f32 v70, v30, v72, v103
	v_fma_f32 v71, v30, v73, v119
	v_fma_f32 v34, v10, v73, v70
	v_fma_f32 v35, v11, v72, v71
	s_waitcnt vmcnt(9)
	ds_write_b64 v146, v[50:51]
	ds_read_b128 v[156:159], v196
	ds_read_b128 v[200:203], v197
	global_load_dwordx2 v[44:45], v[54:55], off
	v_lshl_add_u64 v[54:55], v[54:55], 0, s[20:21]
	global_load_dwordx4 v[78:81], v[56:57], off offset:16 nt
	s_mov_b64 s[22:23], 0x400000
	v_lshl_add_u64 v[56:57], v[56:57], 0, s[22:23]
	v_fma_f32 v70, v30, v34, v120
	v_fma_f32 v71, v30, v35, v226
	v_fma_f32 v72, v10, v35, v70
	v_fma_f32 v73, v11, v34, v71
	v_fma_f32 v70, v30, v72, v121
	v_fma_f32 v71, v30, v73, v227
	v_fma_f32 v34, v10, v73, v70
	v_fma_f32 v35, v11, v72, v71
	v_fma_f32 v70, v30, v34, v122
	v_fma_f32 v71, v30, v35, v228
	v_fma_f32 v72, v10, v35, v70
	v_fma_f32 v73, v11, v34, v71
	v_fma_f32 v70, v30, v72, v123
	v_fma_f32 v71, v30, v73, v229
	v_fma_f32 v34, v10, v73, v70
	v_fma_f32 v35, v11, v72, v71
	s_waitcnt lgkmcnt(0)
; #define LAS __attribute__((address_space(3)))
; __device__ __forceinline__ unsigned cvt_pk_bf16(float lo, float hi) { const f32x2 v = {lo, hi}; return __builtin_bit_cast(unsigned, __builtin_convertvector(v, bfx2_t)); }
; __device__ __forceinline__ void conv_p(const Params& P, int l) {
;     ...
;         for (int q = 0; q < 4; ++q) { u32x4 w; w.x = cvt_pk_bf16(a[q][0], a[q][1]); w.y = cvt_pk_bf16(a[q][2], a[q][3]); w.z = cvt_pk_bf16(b[q][0], b[q][1]); w.w = cvt_pk_bf16(b[q][2], b[q][3]);
;             *(u32x4*)(dst + (i + q * stride) * 8) = w; }
; template <int PASS> __device__ void ssm_pass(const Params& P, int l, LAS unsigned char* lds) {
;     ...
;             u32x2 unext = ucur; if (mt < 63) unext = *(const u32x2*)(zrow + (size_t)(mt + 1) * 16 * DM);
;             const bf16x4 af = __builtin_bit_cast(bf16x4, ucur);
;             f32x4 d[8];
; #pragma unroll
;             for (int t = 0; t < 8; ++t) d[t] = __builtin_amdgcn_mfma_f32_16x16x16bf16_1k(af, bf[t], (f32x4){0.f, 0.f, 0.f, 0.f}, 0, 0, 0);
; #pragma unroll
;             for (int tq = 0; tq < 4; ++tq)
; #pragma unroll
;                 for (int j = 0; j < 4; ++j) *(LAS f32x2*)(BU + (4 * fq + j) * 528 + (16 * tq + fr) * 8) = (f32x2){d[tq][j], d[tq + 4][j]};
;             asm volatile("s_waitcnt lgkmcnt(0)" ::: "memory");
; #pragma unroll
;             for (int j = 0; j < 16; ++j) {
;                 const f32x2 bu = *(const LAS f32x2*)(BU + j * 528 + lane * 8);
;                 sv = __builtin_elementwise_fma(ayn, __builtin_shufflevector(sv, sv, 1, 0), __builtin_elementwise_fma(axx, sv, bu));
	v_mfma_f32_32x32x16_bf16 v[88:103], v[156:159], v[12:15], 0
	v_mfma_f32_32x32x16_bf16 v[104:119], v[156:159], v[20:23], 0
	v_fma_f32 v70, v30, v34, v124
	v_fma_f32 v71, v30, v35, v230
	v_fma_f32 v72, v10, v35, v70
	v_fma_f32 v73, v11, v34, v71
	v_fma_f32 v70, v30, v72, v125
	v_fma_f32 v71, v30, v73, v231
	v_fma_f32 v34, v10, v73, v70
	v_fma_f32 v35, v11, v72, v71
	v_fma_f32 v70, v30, v34, v126
	v_fma_f32 v71, v30, v35, v232
	v_fma_f32 v72, v10, v35, v70
	v_fma_f32 v73, v11, v34, v71
	v_fma_f32 v70, v30, v72, v127
	v_fma_f32 v71, v30, v73, v233
	v_fma_f32 v34, v10, v73, v70
	v_fma_f32 v35, v11, v72, v71
	v_mfma_f32_32x32x16_bf16 v[88:103], v[200:203], v[16:19], v[88:103]
	v_mfma_f32_32x32x16_bf16 v[104:119], v[200:203], v[24:27], v[104:119]
	v_fma_f32 v70, v30, v34, v128
	v_fma_f32 v71, v30, v35, v234
	v_fma_f32 v72, v10, v35, v70
	v_fma_f32 v73, v11, v34, v71
	v_fma_f32 v70, v30, v72, v129
	v_fma_f32 v71, v30, v73, v235
	v_fma_f32 v34, v10, v73, v70
	v_fma_f32 v35, v11, v72, v71
	v_fma_f32 v70, v30, v34, v130
	v_fma_f32 v71, v30, v35, v236
	v_fma_f32 v72, v10, v35, v70
	v_fma_f32 v73, v11, v34, v71
	v_fma_f32 v70, v30, v72, v131
	v_fma_f32 v71, v30, v73, v237
	v_fma_f32 v34, v10, v73, v70
	v_fma_f32 v35, v11, v72, v71
	v_fma_f32 v70, v30, v34, v132
	v_fma_f32 v71, v30, v35, v238
	v_fma_f32 v72, v10, v35, v70
	v_fma_f32 v73, v11, v34, v71
	v_fma_f32 v70, v30, v72, v133
	v_fma_f32 v71, v30, v73, v239
	v_fma_f32 v34, v10, v73, v70
	v_fma_f32 v35, v11, v72, v71
	v_fma_f32 v70, v30, v34, v134
	v_fma_f32 v71, v30, v35, v240
	v_fma_f32 v72, v10, v35, v70
	v_fma_f32 v73, v11, v34, v71
	v_fma_f32 v70, v30, v72, v135
	v_fma_f32 v71, v30, v73, v241
	v_fma_f32 v34, v10, v73, v70
	v_fma_f32 v35, v11, v72, v71
	s_waitcnt vmcnt(9)
	ds_write_b64 v146, v[52:53]
	ds_read_b128 v[156:159], v196
	ds_read_b128 v[200:203], v197
	global_load_dwordx2 v[46:47], v[54:55], off
	v_lshl_add_u64 v[54:55], v[54:55], 0, s[20:21]
	global_load_dwordx2 v[144:145], v[54:55], off
	v_fma_f32 v70, v30, v34, v88
	v_fma_f32 v71, v30, v35, v104
	v_fma_f32 v72, v10, v35, v70
	v_fma_f32 v73, v11, v34, v71
	v_fma_f32 v70, v30, v72, v89
	v_fma_f32 v71, v30, v73, v105
	v_fma_f32 v34, v10, v73, v70
	v_fma_f32 v35, v11, v72, v71
	v_fma_f32 v70, v30, v34, v90
	v_fma_f32 v71, v30, v35, v106
	v_fma_f32 v72, v10, v35, v70
	v_fma_f32 v73, v11, v34, v71
	v_fma_f32 v70, v30, v72, v91
	v_fma_f32 v71, v30, v73, v107
	v_fma_f32 v34, v10, v73, v70
	v_fma_f32 v35, v11, v72, v71
	s_waitcnt lgkmcnt(0)
	v_mfma_f32_32x32x16_bf16 v[120:135], v[156:159], v[12:15], 0
	v_mfma_f32_32x32x16_bf16 v[226:241], v[156:159], v[20:23], 0
	v_fma_f32 v70, v30, v34, v92
	v_fma_f32 v71, v30, v35, v108
	v_fma_f32 v72, v10, v35, v70
	v_fma_f32 v73, v11, v34, v71
	v_fma_f32 v70, v30, v72, v93
	v_fma_f32 v71, v30, v73, v109
	v_fma_f32 v34, v10, v73, v70
	v_fma_f32 v35, v11, v72, v71
	v_fma_f32 v70, v30, v34, v94
	v_fma_f32 v71, v30, v35, v110
	v_fma_f32 v72, v10, v35, v70
	v_fma_f32 v73, v11, v34, v71
	v_fma_f32 v70, v30, v72, v95
	v_fma_f32 v71, v30, v73, v111
	v_fma_f32 v34, v10, v73, v70
	v_fma_f32 v35, v11, v72, v71
	v_mfma_f32_32x32x16_bf16 v[120:135], v[200:203], v[16:19], v[120:135]
	v_mfma_f32_32x32x16_bf16 v[226:241], v[200:203], v[24:27], v[226:241]
	v_fma_f32 v70, v30, v34, v96
	v_fma_f32 v71, v30, v35, v112
	v_fma_f32 v72, v10, v35, v70
	v_fma_f32 v73, v11, v34, v71
	v_fma_f32 v70, v30, v72, v97
	v_fma_f32 v71, v30, v73, v113
	v_fma_f32 v34, v10, v73, v70
	v_fma_f32 v35, v11, v72, v71
	v_fma_f32 v70, v30, v34, v98
	v_fma_f32 v71, v30, v35, v114
	v_fma_f32 v72, v10, v35, v70
	v_fma_f32 v73, v11, v34, v71
	v_fma_f32 v70, v30, v72, v99
	v_fma_f32 v71, v30, v73, v115
	v_fma_f32 v34, v10, v73, v70
	v_fma_f32 v35, v11, v72, v71
	v_fma_f32 v70, v30, v34, v100
	v_fma_f32 v71, v30, v35, v116
	v_fma_f32 v72, v10, v35, v70
	v_fma_f32 v73, v11, v34, v71
	v_fma_f32 v70, v30, v72, v101
	v_fma_f32 v71, v30, v73, v117
	v_fma_f32 v34, v10, v73, v70
	v_fma_f32 v35, v11, v72, v71
	v_fma_f32 v70, v30, v34, v102
	v_fma_f32 v71, v30, v35, v118
	v_fma_f32 v72, v10, v35, v70
	v_fma_f32 v73, v11, v34, v71
	v_fma_f32 v70, v30, v72, v103
	v_fma_f32 v71, v30, v73, v119
	v_fma_f32 v34, v10, v73, v70
	v_fma_f32 v35, v11, v72, v71
	s_waitcnt vmcnt(9)
	ds_write_b64 v146, v[36:37]
	ds_read_b128 v[156:159], v196
	ds_read_b128 v[200:203], v197
	global_load_dwordx2 v[48:49], v[54:55], off
	v_lshl_add_u64 v[54:55], v[54:55], 0, s[20:21]
	v_cvt_pk_bf16_f32 v82, v60, v61
	v_cvt_pk_bf16_f32 v83, v62, v63
	v_cvt_pk_bf16_f32 v84, v64, v65
	v_cvt_pk_bf16_f32 v85, v66, v67
	global_store_dwordx4 v[58:59], v[82:85], off
	s_mov_b64 s[22:23], 0x200000
	v_lshl_add_u64 v[58:59], v[58:59], 0, s[22:23]
	v_fma_f32 v70, v30, v34, v120
	v_fma_f32 v71, v30, v35, v226
	v_fma_f32 v72, v10, v35, v70
	v_fma_f32 v73, v11, v34, v71
	v_fma_f32 v70, v30, v72, v121
	v_fma_f32 v71, v30, v73, v227
	v_fma_f32 v34, v10, v73, v70
	v_fma_f32 v35, v11, v72, v71
	v_fma_f32 v70, v30, v34, v122
	v_fma_f32 v71, v30, v35, v228
	v_fma_f32 v72, v10, v35, v70
	v_fma_f32 v73, v11, v34, v71
	v_fma_f32 v70, v30, v72, v123
	v_fma_f32 v71, v30, v73, v229
	v_fma_f32 v34, v10, v73, v70
	v_fma_f32 v35, v11, v72, v71
	s_waitcnt lgkmcnt(0)
	v_mfma_f32_32x32x16_bf16 v[88:103], v[156:159], v[12:15], 0
	v_mfma_f32_32x32x16_bf16 v[104:119], v[156:159], v[20:23], 0
	v_fma_f32 v70, v30, v34, v124
	v_fma_f32 v71, v30, v35, v230
	v_fma_f32 v72, v10, v35, v70
	v_fma_f32 v73, v11, v34, v71
	v_fma_f32 v70, v30, v72, v125
	v_fma_f32 v71, v30, v73, v231
	v_fma_f32 v34, v10, v73, v70
	v_fma_f32 v35, v11, v72, v71
	v_fma_f32 v70, v30, v34, v126
	v_fma_f32 v71, v30, v35, v232
	v_fma_f32 v72, v10, v35, v70
	v_fma_f32 v73, v11, v34, v71
	v_fma_f32 v70, v30, v72, v127
	v_fma_f32 v71, v30, v73, v233
	v_fma_f32 v34, v10, v73, v70
	v_fma_f32 v35, v11, v72, v71
	v_mfma_f32_32x32x16_bf16 v[88:103], v[200:203], v[16:19], v[88:103]
	v_mfma_f32_32x32x16_bf16 v[104:119], v[200:203], v[24:27], v[104:119]
	v_fma_f32 v70, v30, v34, v128
	v_fma_f32 v71, v30, v35, v234
	v_fma_f32 v72, v10, v35, v70
	v_fma_f32 v73, v11, v34, v71
	v_fma_f32 v70, v30, v72, v129
	v_fma_f32 v71, v30, v73, v235
	v_fma_f32 v34, v10, v73, v70
	v_fma_f32 v35, v11, v72, v71
	v_fma_f32 v70, v30, v34, v130
	v_fma_f32 v71, v30, v35, v236
	v_fma_f32 v72, v10, v35, v70
	v_fma_f32 v73, v11, v34, v71
	v_fma_f32 v70, v30, v72, v131
	v_fma_f32 v71, v30, v73, v237
	v_fma_f32 v34, v10, v73, v70
	v_fma_f32 v35, v11, v72, v71
	v_fma_f32 v70, v30, v34, v132
	v_fma_f32 v71, v30, v35, v238
	v_fma_f32 v72, v10, v35, v70
	v_fma_f32 v73, v11, v34, v71
	v_fma_f32 v70, v30, v72, v133
	v_fma_f32 v71, v30, v73, v239
	v_fma_f32 v34, v10, v73, v70
	v_fma_f32 v35, v11, v72, v71
	v_fma_f32 v70, v30, v34, v134
	v_fma_f32 v71, v30, v35, v240
	v_fma_f32 v72, v10, v35, v70
	v_fma_f32 v73, v11, v34, v71
	v_fma_f32 v70, v30, v72, v135
	v_fma_f32 v71, v30, v73, v241
	v_fma_f32 v34, v10, v73, v70
	v_fma_f32 v35, v11, v72, v71
	s_add_u32 s12, s12, 8
	s_cmp_eq_u32 s12, 64
	s_cbranch_scc0 .Lp1_loop
; __device__ __forceinline__ unsigned cvt_pk_bf16(float lo, float hi) { const f32x2 v = {lo, hi}; return __builtin_bit_cast(unsigned, __builtin_convertvector(v, bfx2_t)); }
; __device__ __forceinline__ void conv_p(const Params& P, int l) {
;     ...
;         for (int q = 0; q < 4; ++q) { a[q] = *(const f32x4*)(src + (i + q * stride) * 8); b[q] = *(const f32x4*)(src + (i + q * stride) * 8 + 4); }
; #pragma unroll
;         for (int q = 0; q < 4; ++q) { u32x4 w; w.x = cvt_pk_bf16(a[q][0], a[q][1]); w.y = cvt_pk_bf16(a[q][2], a[q][3]); w.z = cvt_pk_bf16(b[q][0], b[q][1]); w.w = cvt_pk_bf16(b[q][2], b[q][3]);
;             *(u32x4*)(dst + (i + q * stride) * 8) = w; }
	s_waitcnt vmcnt(0)
	v_cvt_pk_bf16_f32 v82, v74, v75
	v_cvt_pk_bf16_f32 v83, v76, v77
	v_cvt_pk_bf16_f32 v84, v78, v79
	v_cvt_pk_bf16_f32 v85, v80, v81
	global_store_dwordx4 v[58:59], v[82:85], off
	s_mov_b64 s[22:23], 0x200000
	v_lshl_add_u64 v[58:59], v[58:59], 0, s[22:23]
	s_waitcnt lgkmcnt(0)
	s_branch .LBB0_338
